# GEMM K-loops: the s_setprio 0 / s_setprio 1 flip between the two 16-MFMA groups of each 32-MFMA block deleted (priority stays raised for the whole block); everything else as v31
# speedup vs baseline: 1.0229x; 1.0011x over previous
; #define PG8_STAGE(bufoff, gbase, voff) do { _Pragma("unroll") for (int _i = 0; _i < 2; ++_i) \
;         __builtin_amdgcn_global_load_lds((const unsigned*)((const char*)(gbase) + (voff)[_i]), (PG8_LAS unsigned*)(lds + (bufoff) + ldsw + _i * 8192), 16, 0, 0); } while (0)
; #define PG8_LDA(dst, b, h) do { _Pragma("unroll") for (int m = 0; m < 4; ++m) _Pragma("unroll") for (int k = 0; k < 2; ++k) dst[m][k] = *(const PG8_LAS bf16x8*)(lds + PG8_SA(b, h) + aoff + m * 2048 + k * 1024); } while (0)
; #define PG8_LDB(dst, b, h) do { _Pragma("unroll") for (int n = 0; n < 2; ++n) _Pragma("unroll") for (int k = 0; k < 2; ++k) dst[n][k] = *(const PG8_LAS bf16x8*)(lds + PG8_SB(b, h) + boff + n * 2048 + k * 1024); } while (0)
; #define PG8_MMA(ai, bj, At, Bt) do { __builtin_amdgcn_s_setprio(1); _Pragma("unroll") for (int m = 0; m < 4; ++m) _Pragma("unroll") for (int n = 0; n < 2; ++n) _Pragma("unroll") for (int k = 0; k < 2; ++k) \
;         acc[ai][bj][m][n] = __builtin_amdgcn_mfma_f32_16x16x32_bf16(Bt[n][k], At[m][k], acc[ai][bj][m][n], 0, 0, 0); __builtin_amdgcn_s_setprio(0); } while (0)
; #define PG8_BAR __builtin_amdgcn_s_barrier()
; template <class Epi, class Sched, bool ALIGN_EPI = false, bool SP2 = false>
; __device__ __forceinline__ void gemm_phase(PG8_LAS unsigned char* lds, const Gemm g, const Sched& S, const Epi& E) {
;     ...
;             if constexpr (SP2) {
;             PG8_LDB(B0, 0, 0); PG8_LDB(B1, 0, 1); PG8_SCHED; PG8_LDA(At, 0, 0); PG8_STAGE(PG8_SA(1, 1), a1 + hstep, voffA);
;             PG8_WAIT_V(8); PG8_WAIT_L(0); PG8_BAR; PG8_MMA(0, 0, At, B0); PG8_MMA(0, 1, At, B1); PG8_BAR; PG8_SCHED;
;             PG8_LDA(At, 0, 1); PG8_STAGE(PG8_SB(0, 0), b2, voffB); PG8_STAGE(PG8_SB(0, 1), b2 + hstep, voffB); PG8_STAGE(PG8_SA(0, 0), a2, voffA);
;             PG8_WAIT_V(8); PG8_WAIT_L(0); PG8_BAR; PG8_MMA(1, 0, At, B0); PG8_MMA(1, 1, At, B1); PG8_BAR; PG8_SCHED;
;             PG8_LDB(B0, 1, 0); PG8_LDB(B1, 1, 1); PG8_SCHED; PG8_LDA(At, 1, 0); PG8_STAGE(PG8_SA(0, 1), a2 + hstep, voffA);
;             PG8_WAIT_V(8); PG8_WAIT_L(0); PG8_BAR; PG8_MMA(0, 0, At, B0); PG8_MMA(0, 1, At, B1); PG8_BAR; PG8_SCHED;
;             PG8_LDA(At, 1, 1); PG8_STAGE(PG8_SB(1, 0), b3, voffB); PG8_STAGE(PG8_SB(1, 1), b3 + hstep, voffB); PG8_STAGE(PG8_SA(1, 0), a3, voffA);
;             PG8_WAIT_V(8); PG8_WAIT_L(0); PG8_BAR; PG8_MMA(1, 0, At, B0); PG8_MMA(1, 1, At, B1); PG8_BAR; PG8_SCHED;
.LBB0_119:
	ds_read_b128 v[154:157], v151
	ds_read_b128 v[158:161], v151 offset:1024
	ds_read_b128 v[162:165], v151 offset:2048
	ds_read_b128 v[166:169], v151 offset:3072
	ds_read_b128 v[170:173], v152
	ds_read_b128 v[174:177], v152 offset:1024
	ds_read_b128 v[178:181], v152 offset:2048
	ds_read_b128 v[182:185], v152 offset:3072
	s_add_u32 s70, s68, 0xfff80080
	s_addc_u32 s71, s69, -1
	s_cmp_eq_u32 s93, 28
	s_cselect_b32 s73, s35, s71
	s_cselect_b32 s72, s89, s70
	s_cselect_b32 s71, s21, s92
	s_cselect_b32 s70, s90, s91
	v_lshl_add_u64 v[218:219], s[68:69], 0, v[136:137]
	s_add_i32 m0, s19, 0xc000
	ds_read_b128 v[186:189], v153
	ds_read_b128 v[190:193], v153 offset:1024
	ds_read_b128 v[194:197], v153 offset:2048
	ds_read_b128 v[198:201], v153 offset:3072
	ds_read_b128 v[202:205], v153 offset:4096
	ds_read_b128 v[206:209], v153 offset:5120
	ds_read_b128 v[210:213], v153 offset:6144
	ds_read_b128 v[214:217], v153 offset:7168
	global_load_lds_dwordx4 v[218:219], off
	v_lshl_add_u64 v[218:219], s[68:69], 0, v[138:139]
	s_add_i32 m0, s19, 0xe000
	s_nop 0
	global_load_lds_dwordx4 v[218:219], off
	s_waitcnt vmcnt(8)
	s_waitcnt lgkmcnt(0)
	s_barrier
	s_setprio 1
	s_waitcnt lgkmcnt(0)
	v_mfma_f32_16x16x32_bf16 v[124:127], v[154:157], v[186:189], v[124:127]
	v_mfma_f32_16x16x32_bf16 v[120:123], v[162:165], v[186:189], v[120:123]
	v_mfma_f32_16x16x32_bf16 v[116:119], v[154:157], v[194:197], v[116:119]
	v_mfma_f32_16x16x32_bf16 v[112:115], v[162:165], v[194:197], v[112:115]
	v_mfma_f32_16x16x32_bf16 v[100:103], v[154:157], v[202:205], v[100:103]
	v_mfma_f32_16x16x32_bf16 v[96:99], v[162:165], v[202:205], v[96:99]
	v_mfma_f32_16x16x32_bf16 v[84:87], v[154:157], v[210:213], v[84:87]
	v_mfma_f32_16x16x32_bf16 v[80:83], v[162:165], v[210:213], v[80:83]
	v_mfma_f32_16x16x32_bf16 v[124:127], v[158:161], v[190:193], v[124:127]
	v_mfma_f32_16x16x32_bf16 v[120:123], v[166:169], v[190:193], v[120:123]
	v_mfma_f32_16x16x32_bf16 v[116:119], v[158:161], v[198:201], v[116:119]
	v_mfma_f32_16x16x32_bf16 v[112:115], v[166:169], v[198:201], v[112:115]
	v_mfma_f32_16x16x32_bf16 v[100:103], v[158:161], v[206:209], v[100:103]
	v_mfma_f32_16x16x32_bf16 v[96:99], v[166:169], v[206:209], v[96:99]
	v_mfma_f32_16x16x32_bf16 v[84:87], v[158:161], v[214:217], v[84:87]
	v_mfma_f32_16x16x32_bf16 v[80:83], v[166:169], v[214:217], v[80:83]
	v_mfma_f32_16x16x32_bf16 v[108:111], v[170:173], v[186:189], v[108:111]
	v_mfma_f32_16x16x32_bf16 v[104:107], v[178:181], v[186:189], v[104:107]
	v_mfma_f32_16x16x32_bf16 v[92:95], v[170:173], v[194:197], v[92:95]
	v_mfma_f32_16x16x32_bf16 v[88:91], v[178:181], v[194:197], v[88:91]
	v_mfma_f32_16x16x32_bf16 v[76:79], v[170:173], v[202:205], v[76:79]
	v_mfma_f32_16x16x32_bf16 v[72:75], v[178:181], v[202:205], v[72:75]
	v_mfma_f32_16x16x32_bf16 v[68:71], v[170:173], v[210:213], v[68:71]
	v_mfma_f32_16x16x32_bf16 v[64:67], v[178:181], v[210:213], v[64:67]
	v_mfma_f32_16x16x32_bf16 v[108:111], v[174:177], v[190:193], v[108:111]
	v_mfma_f32_16x16x32_bf16 v[104:107], v[182:185], v[190:193], v[104:107]
	v_mfma_f32_16x16x32_bf16 v[92:95], v[174:177], v[198:201], v[92:95]
	v_mfma_f32_16x16x32_bf16 v[88:91], v[182:185], v[198:201], v[88:91]
	v_mfma_f32_16x16x32_bf16 v[76:79], v[174:177], v[206:209], v[76:79]
	v_mfma_f32_16x16x32_bf16 v[72:75], v[182:185], v[206:209], v[72:75]
	v_mfma_f32_16x16x32_bf16 v[68:71], v[174:177], v[214:217], v[68:71]
	v_mfma_f32_16x16x32_bf16 v[64:67], v[182:185], v[214:217], v[64:67]
	s_setprio 0
	s_barrier
	s_add_i32 s94, s86, s55
	v_lshl_add_u64 v[218:219], s[70:71], 0, v[130:131]
	s_mov_b32 m0, s94
	ds_read_b128 v[186:189], v153 offset:16384
	ds_read_b128 v[190:193], v153 offset:17408
	ds_read_b128 v[194:197], v153 offset:18432
	ds_read_b128 v[198:201], v153 offset:19456
	ds_read_b128 v[202:205], v153 offset:20480
	ds_read_b128 v[206:209], v153 offset:21504
	ds_read_b128 v[210:213], v153 offset:22528
	ds_read_b128 v[214:217], v153 offset:23552
	global_load_lds_dwordx4 v[218:219], off
	s_add_i32 m0, s94, 0x2000
	s_add_u32 s94, s70, 0x80000
	v_lshl_add_u64 v[220:221], s[70:71], 0, v[134:135]
	s_addc_u32 s95, s71, 0
	s_add_i32 s96, s87, s55
	global_load_lds_dwordx4 v[220:221], off
	v_lshl_add_u64 v[222:223], s[94:95], 0, v[130:131]
	s_mov_b32 m0, s96
	v_lshl_add_u64 v[224:225], s[72:73], 0, v[132:133]
	global_load_lds_dwordx4 v[222:223], off
	v_lshl_add_u64 v[222:223], s[94:95], 0, v[134:135]
	s_add_i32 m0, s96, 0x2000
	s_nop 0
	global_load_lds_dwordx4 v[222:223], off
	v_lshl_add_u64 v[222:223], s[72:73], 0, v[128:129]
	s_mov_b32 m0, s19
	s_nop 0
	global_load_lds_dwordx4 v[222:223], off
	s_mov_b32 m0, s75
	s_nop 0
	global_load_lds_dwordx4 v[224:225], off
	s_waitcnt vmcnt(8)
	s_waitcnt lgkmcnt(0)
	s_barrier
; #define PG8_STAGE(bufoff, gbase, voff) do { _Pragma("unroll") for (int _i = 0; _i < 2; ++_i) \
;         __builtin_amdgcn_global_load_lds((const unsigned*)((const char*)(gbase) + (voff)[_i]), (PG8_LAS unsigned*)(lds + (bufoff) + ldsw + _i * 8192), 16, 0, 0); } while (0)
; #define PG8_LDA(dst, b, h) do { _Pragma("unroll") for (int m = 0; m < 4; ++m) _Pragma("unroll") for (int k = 0; k < 2; ++k) dst[m][k] = *(const PG8_LAS bf16x8*)(lds + PG8_SA(b, h) + aoff + m * 2048 + k * 1024); } while (0)
; #define PG8_LDB(dst, b, h) do { _Pragma("unroll") for (int n = 0; n < 2; ++n) _Pragma("unroll") for (int k = 0; k < 2; ++k) dst[n][k] = *(const PG8_LAS bf16x8*)(lds + PG8_SB(b, h) + boff + n * 2048 + k * 1024); } while (0)
; #define PG8_MMA(ai, bj, At, Bt) do { __builtin_amdgcn_s_setprio(1); _Pragma("unroll") for (int m = 0; m < 4; ++m) _Pragma("unroll") for (int n = 0; n < 2; ++n) _Pragma("unroll") for (int k = 0; k < 2; ++k) \
;         acc[ai][bj][m][n] = __builtin_amdgcn_mfma_f32_16x16x32_bf16(Bt[n][k], At[m][k], acc[ai][bj][m][n], 0, 0, 0); __builtin_amdgcn_s_setprio(0); } while (0)
; #define PG8_BAR __builtin_amdgcn_s_barrier()
; template <class Epi, class Sched, bool ALIGN_EPI = false, bool SP2 = false>
; __device__ __forceinline__ void gemm_phase(PG8_LAS unsigned char* lds, const Gemm g, const Sched& S, const Epi& E) {
;     ...
;             if constexpr (SP2) {
;             PG8_LDB(B0, 0, 0); PG8_LDB(B1, 0, 1); PG8_SCHED; PG8_LDA(At, 0, 0); PG8_STAGE(PG8_SA(1, 1), a1 + hstep, voffA);
;             PG8_WAIT_V(8); PG8_WAIT_L(0); PG8_BAR; PG8_MMA(0, 0, At, B0); PG8_MMA(0, 1, At, B1); PG8_BAR; PG8_SCHED;
;             PG8_LDA(At, 0, 1); PG8_STAGE(PG8_SB(0, 0), b2, voffB); PG8_STAGE(PG8_SB(0, 1), b2 + hstep, voffB); PG8_STAGE(PG8_SA(0, 0), a2, voffA);
;             PG8_WAIT_V(8); PG8_WAIT_L(0); PG8_BAR; PG8_MMA(1, 0, At, B0); PG8_MMA(1, 1, At, B1); PG8_BAR; PG8_SCHED;
;             PG8_LDB(B0, 1, 0); PG8_LDB(B1, 1, 1); PG8_SCHED; PG8_LDA(At, 1, 0); PG8_STAGE(PG8_SA(0, 1), a2 + hstep, voffA);
;             PG8_WAIT_V(8); PG8_WAIT_L(0); PG8_BAR; PG8_MMA(0, 0, At, B0); PG8_MMA(0, 1, At, B1); PG8_BAR; PG8_SCHED;
;             PG8_LDA(At, 1, 1); PG8_STAGE(PG8_SB(1, 0), b3, voffB); PG8_STAGE(PG8_SB(1, 1), b3 + hstep, voffB); PG8_STAGE(PG8_SA(1, 0), a3, voffA);
;             PG8_WAIT_V(8); PG8_WAIT_L(0); PG8_BAR; PG8_MMA(1, 0, At, B0); PG8_MMA(1, 1, At, B1); PG8_BAR; PG8_SCHED;
	s_setprio 1
	s_waitcnt lgkmcnt(0)
	v_mfma_f32_16x16x32_bf16 v[60:63], v[154:157], v[186:189], v[60:63]
	v_mfma_f32_16x16x32_bf16 v[56:59], v[162:165], v[186:189], v[56:59]
	v_mfma_f32_16x16x32_bf16 v[52:55], v[154:157], v[194:197], v[52:55]
	v_mfma_f32_16x16x32_bf16 v[48:51], v[162:165], v[194:197], v[48:51]
	v_mfma_f32_16x16x32_bf16 v[36:39], v[154:157], v[202:205], v[36:39]
	v_mfma_f32_16x16x32_bf16 v[32:35], v[162:165], v[202:205], v[32:35]
	v_mfma_f32_16x16x32_bf16 v[20:23], v[154:157], v[210:213], v[20:23]
	v_mfma_f32_16x16x32_bf16 v[16:19], v[162:165], v[210:213], v[16:19]
	v_mfma_f32_16x16x32_bf16 v[60:63], v[158:161], v[190:193], v[60:63]
	v_mfma_f32_16x16x32_bf16 v[56:59], v[166:169], v[190:193], v[56:59]
	v_mfma_f32_16x16x32_bf16 v[52:55], v[158:161], v[198:201], v[52:55]
	v_mfma_f32_16x16x32_bf16 v[48:51], v[166:169], v[198:201], v[48:51]
	v_mfma_f32_16x16x32_bf16 v[36:39], v[158:161], v[206:209], v[36:39]
	v_mfma_f32_16x16x32_bf16 v[32:35], v[166:169], v[206:209], v[32:35]
	v_mfma_f32_16x16x32_bf16 v[20:23], v[158:161], v[214:217], v[20:23]
	v_mfma_f32_16x16x32_bf16 v[16:19], v[166:169], v[214:217], v[16:19]
	v_mfma_f32_16x16x32_bf16 v[44:47], v[170:173], v[186:189], v[44:47]
	v_mfma_f32_16x16x32_bf16 v[40:43], v[178:181], v[186:189], v[40:43]
	v_mfma_f32_16x16x32_bf16 v[28:31], v[170:173], v[194:197], v[28:31]
	v_mfma_f32_16x16x32_bf16 v[24:27], v[178:181], v[194:197], v[24:27]
	v_mfma_f32_16x16x32_bf16 v[12:15], v[170:173], v[202:205], v[12:15]
	v_mfma_f32_16x16x32_bf16 v[8:11], v[178:181], v[202:205], v[8:11]
	v_mfma_f32_16x16x32_bf16 v[4:7], v[170:173], v[210:213], v[4:7]
	v_mfma_f32_16x16x32_bf16 v[0:3], v[178:181], v[210:213], v[0:3]
	v_mfma_f32_16x16x32_bf16 v[44:47], v[174:177], v[190:193], v[44:47]
	v_mfma_f32_16x16x32_bf16 v[40:43], v[182:185], v[190:193], v[40:43]
	v_mfma_f32_16x16x32_bf16 v[28:31], v[174:177], v[198:201], v[28:31]
	v_mfma_f32_16x16x32_bf16 v[24:27], v[182:185], v[198:201], v[24:27]
	v_mfma_f32_16x16x32_bf16 v[12:15], v[174:177], v[206:209], v[12:15]
	v_mfma_f32_16x16x32_bf16 v[8:11], v[182:185], v[206:209], v[8:11]
	v_mfma_f32_16x16x32_bf16 v[4:7], v[174:177], v[214:217], v[4:7]
	v_mfma_f32_16x16x32_bf16 v[0:3], v[182:185], v[214:217], v[0:3]
	s_setprio 0
	s_barrier
	s_add_i32 s94, 0, 0x18000
	s_add_i32 s95, 0, 0x1c000
	v_add_u32_e32 v166, s94, v149
	v_add_u32_e32 v182, s95, v149
	ds_read_b128 v[154:157], v166
	ds_read_b128 v[158:161], v166 offset:1024
	ds_read_b128 v[162:165], v166 offset:2048
	ds_read_b128 v[166:169], v166 offset:3072
	ds_read_b128 v[170:173], v182
	ds_read_b128 v[174:177], v182 offset:1024
	ds_read_b128 v[178:181], v182 offset:2048
	ds_read_b128 v[182:185], v182 offset:3072
	s_add_u32 s72, s72, 0x80000
	s_addc_u32 s73, s73, 0
	s_mov_b32 m0, s76
	v_lshl_add_u64 v[226:227], s[72:73], 0, v[128:129]
	ds_read_b128 v[186:189], v153 offset:32768
	ds_read_b128 v[190:193], v153 offset:33792
	ds_read_b128 v[194:197], v153 offset:34816
	ds_read_b128 v[198:201], v153 offset:35840
	ds_read_b128 v[202:205], v153 offset:36864
	ds_read_b128 v[206:209], v153 offset:37888
	ds_read_b128 v[210:213], v153 offset:38912
	ds_read_b128 v[214:217], v153 offset:39936
	global_load_lds_dwordx4 v[226:227], off
	v_lshl_add_u64 v[226:227], s[72:73], 0, v[132:133]
	s_mov_b32 m0, s77
	s_nop 0
	global_load_lds_dwordx4 v[226:227], off
	s_waitcnt vmcnt(8)
	s_waitcnt lgkmcnt(0)
	s_barrier
	s_setprio 1
	s_waitcnt lgkmcnt(0)
	v_mfma_f32_16x16x32_bf16 v[124:127], v[154:157], v[186:189], v[124:127]
	v_mfma_f32_16x16x32_bf16 v[120:123], v[162:165], v[186:189], v[120:123]
	v_mfma_f32_16x16x32_bf16 v[116:119], v[154:157], v[194:197], v[116:119]
	v_mfma_f32_16x16x32_bf16 v[112:115], v[162:165], v[194:197], v[112:115]
	v_mfma_f32_16x16x32_bf16 v[100:103], v[154:157], v[202:205], v[100:103]
	v_mfma_f32_16x16x32_bf16 v[96:99], v[162:165], v[202:205], v[96:99]
	v_mfma_f32_16x16x32_bf16 v[84:87], v[154:157], v[210:213], v[84:87]
	v_mfma_f32_16x16x32_bf16 v[80:83], v[162:165], v[210:213], v[80:83]
	v_mfma_f32_16x16x32_bf16 v[124:127], v[158:161], v[190:193], v[124:127]
	v_mfma_f32_16x16x32_bf16 v[120:123], v[166:169], v[190:193], v[120:123]
	v_mfma_f32_16x16x32_bf16 v[116:119], v[158:161], v[198:201], v[116:119]
	v_mfma_f32_16x16x32_bf16 v[112:115], v[166:169], v[198:201], v[112:115]
	v_mfma_f32_16x16x32_bf16 v[100:103], v[158:161], v[206:209], v[100:103]
	v_mfma_f32_16x16x32_bf16 v[96:99], v[166:169], v[206:209], v[96:99]
	v_mfma_f32_16x16x32_bf16 v[84:87], v[158:161], v[214:217], v[84:87]
	v_mfma_f32_16x16x32_bf16 v[80:83], v[166:169], v[214:217], v[80:83]
	v_mfma_f32_16x16x32_bf16 v[108:111], v[170:173], v[186:189], v[108:111]
	v_mfma_f32_16x16x32_bf16 v[104:107], v[178:181], v[186:189], v[104:107]
	v_mfma_f32_16x16x32_bf16 v[92:95], v[170:173], v[194:197], v[92:95]
	v_mfma_f32_16x16x32_bf16 v[88:91], v[178:181], v[194:197], v[88:91]
	v_mfma_f32_16x16x32_bf16 v[76:79], v[170:173], v[202:205], v[76:79]
	v_mfma_f32_16x16x32_bf16 v[72:75], v[178:181], v[202:205], v[72:75]
	v_mfma_f32_16x16x32_bf16 v[68:71], v[170:173], v[210:213], v[68:71]
	v_mfma_f32_16x16x32_bf16 v[64:67], v[178:181], v[210:213], v[64:67]
	v_mfma_f32_16x16x32_bf16 v[108:111], v[174:177], v[190:193], v[108:111]
	v_mfma_f32_16x16x32_bf16 v[104:107], v[182:185], v[190:193], v[104:107]
	v_mfma_f32_16x16x32_bf16 v[92:95], v[174:177], v[198:201], v[92:95]
	v_mfma_f32_16x16x32_bf16 v[88:91], v[182:185], v[198:201], v[88:91]
	v_mfma_f32_16x16x32_bf16 v[76:79], v[174:177], v[206:209], v[76:79]
	v_mfma_f32_16x16x32_bf16 v[72:75], v[182:185], v[206:209], v[72:75]
	v_mfma_f32_16x16x32_bf16 v[68:71], v[174:177], v[214:217], v[68:71]
	v_mfma_f32_16x16x32_bf16 v[64:67], v[182:185], v[214:217], v[64:67]
	s_setprio 0
	s_barrier
; #define PG8_STAGE(bufoff, gbase, voff) do { _Pragma("unroll") for (int _i = 0; _i < 2; ++_i) \
;         __builtin_amdgcn_global_load_lds((const unsigned*)((const char*)(gbase) + (voff)[_i]), (PG8_LAS unsigned*)(lds + (bufoff) + ldsw + _i * 8192), 16, 0, 0); } while (0)
; #define PG8_LDA(dst, b, h) do { _Pragma("unroll") for (int m = 0; m < 4; ++m) _Pragma("unroll") for (int k = 0; k < 2; ++k) dst[m][k] = *(const PG8_LAS bf16x8*)(lds + PG8_SA(b, h) + aoff + m * 2048 + k * 1024); } while (0)
; #define PG8_LDB(dst, b, h) do { _Pragma("unroll") for (int n = 0; n < 2; ++n) _Pragma("unroll") for (int k = 0; k < 2; ++k) dst[n][k] = *(const PG8_LAS bf16x8*)(lds + PG8_SB(b, h) + boff + n * 2048 + k * 1024); } while (0)
; #define PG8_MMA(ai, bj, At, Bt) do { __builtin_amdgcn_s_setprio(1); _Pragma("unroll") for (int m = 0; m < 4; ++m) _Pragma("unroll") for (int n = 0; n < 2; ++n) _Pragma("unroll") for (int k = 0; k < 2; ++k) \
;         acc[ai][bj][m][n] = __builtin_amdgcn_mfma_f32_16x16x32_bf16(Bt[n][k], At[m][k], acc[ai][bj][m][n], 0, 0, 0); __builtin_amdgcn_s_setprio(0); } while (0)
; #define PG8_BAR __builtin_amdgcn_s_barrier()
; template <class Epi, class Sched, bool ALIGN_EPI = false, bool SP2 = false>
; __device__ __forceinline__ void gemm_phase(PG8_LAS unsigned char* lds, const Gemm g, const Sched& S, const Epi& E) {
;     ...
;             if constexpr (SP2) {
;             PG8_LDB(B0, 0, 0); PG8_LDB(B1, 0, 1); PG8_SCHED; PG8_LDA(At, 0, 0); PG8_STAGE(PG8_SA(1, 1), a1 + hstep, voffA);
;             PG8_WAIT_V(8); PG8_WAIT_L(0); PG8_BAR; PG8_MMA(0, 0, At, B0); PG8_MMA(0, 1, At, B1); PG8_BAR; PG8_SCHED;
;             PG8_LDA(At, 0, 1); PG8_STAGE(PG8_SB(0, 0), b2, voffB); PG8_STAGE(PG8_SB(0, 1), b2 + hstep, voffB); PG8_STAGE(PG8_SA(0, 0), a2, voffA);
;             PG8_WAIT_V(8); PG8_WAIT_L(0); PG8_BAR; PG8_MMA(1, 0, At, B0); PG8_MMA(1, 1, At, B1); PG8_BAR; PG8_SCHED;
;             PG8_LDB(B0, 1, 0); PG8_LDB(B1, 1, 1); PG8_SCHED; PG8_LDA(At, 1, 0); PG8_STAGE(PG8_SA(0, 1), a2 + hstep, voffA);
;             PG8_WAIT_V(8); PG8_WAIT_L(0); PG8_BAR; PG8_MMA(0, 0, At, B0); PG8_MMA(0, 1, At, B1); PG8_BAR; PG8_SCHED;
;             PG8_LDA(At, 1, 1); PG8_STAGE(PG8_SB(1, 0), b3, voffB); PG8_STAGE(PG8_SB(1, 1), b3 + hstep, voffB); PG8_STAGE(PG8_SA(1, 0), a3, voffA);
;             PG8_WAIT_V(8); PG8_WAIT_L(0); PG8_BAR; PG8_MMA(1, 0, At, B0); PG8_MMA(1, 1, At, B1); PG8_BAR; PG8_SCHED;
	s_add_i32 s72, s94, s55
	v_lshl_add_u64 v[218:219], v[218:219], 0, s[10:11]
	s_mov_b32 m0, s72
	ds_read_b128 v[186:189], v153 offset:49152
	ds_read_b128 v[190:193], v153 offset:50176
	ds_read_b128 v[194:197], v153 offset:51200
	ds_read_b128 v[198:201], v153 offset:52224
	ds_read_b128 v[202:205], v153 offset:53248
	ds_read_b128 v[206:209], v153 offset:54272
	ds_read_b128 v[210:213], v153 offset:55296
	ds_read_b128 v[214:217], v153 offset:56320
	global_load_lds_dwordx4 v[218:219], off
	s_add_i32 m0, s72, 0x2000
	s_add_u32 s70, s70, 0x80080
	v_lshl_add_u64 v[218:219], v[220:221], 0, s[10:11]
	s_addc_u32 s71, s71, 0
	s_add_i32 s72, s95, s55
	global_load_lds_dwordx4 v[218:219], off
	v_lshl_add_u64 v[218:219], s[70:71], 0, v[130:131]
	s_mov_b32 m0, s72
	s_nop 0
	global_load_lds_dwordx4 v[218:219], off
	v_lshl_add_u64 v[218:219], s[70:71], 0, v[134:135]
	s_add_i32 m0, s72, 0x2000
	s_nop 0
	global_load_lds_dwordx4 v[218:219], off
	v_lshl_add_u64 v[218:219], v[222:223], 0, s[10:11]
	s_mov_b32 m0, s79
	s_nop 0
	global_load_lds_dwordx4 v[218:219], off
	v_lshl_add_u64 v[218:219], v[224:225], 0, s[10:11]
	s_mov_b32 m0, s80
	s_nop 0
	global_load_lds_dwordx4 v[218:219], off
	s_waitcnt vmcnt(8)
	s_waitcnt lgkmcnt(0)
	s_barrier
	s_setprio 1
	s_waitcnt lgkmcnt(0)
	v_mfma_f32_16x16x32_bf16 v[60:63], v[154:157], v[186:189], v[60:63]
	v_mfma_f32_16x16x32_bf16 v[56:59], v[162:165], v[186:189], v[56:59]
	v_mfma_f32_16x16x32_bf16 v[52:55], v[154:157], v[194:197], v[52:55]
	v_mfma_f32_16x16x32_bf16 v[48:51], v[162:165], v[194:197], v[48:51]
	v_mfma_f32_16x16x32_bf16 v[36:39], v[154:157], v[202:205], v[36:39]
	v_mfma_f32_16x16x32_bf16 v[32:35], v[162:165], v[202:205], v[32:35]
	v_mfma_f32_16x16x32_bf16 v[20:23], v[154:157], v[210:213], v[20:23]
	v_mfma_f32_16x16x32_bf16 v[16:19], v[162:165], v[210:213], v[16:19]
	v_mfma_f32_16x16x32_bf16 v[60:63], v[158:161], v[190:193], v[60:63]
	v_mfma_f32_16x16x32_bf16 v[56:59], v[166:169], v[190:193], v[56:59]
	v_mfma_f32_16x16x32_bf16 v[52:55], v[158:161], v[198:201], v[52:55]
	v_mfma_f32_16x16x32_bf16 v[48:51], v[166:169], v[198:201], v[48:51]
	v_mfma_f32_16x16x32_bf16 v[36:39], v[158:161], v[206:209], v[36:39]
	v_mfma_f32_16x16x32_bf16 v[32:35], v[166:169], v[206:209], v[32:35]
	v_mfma_f32_16x16x32_bf16 v[20:23], v[158:161], v[214:217], v[20:23]
	v_mfma_f32_16x16x32_bf16 v[16:19], v[166:169], v[214:217], v[16:19]
	v_mfma_f32_16x16x32_bf16 v[44:47], v[170:173], v[186:189], v[44:47]
	v_mfma_f32_16x16x32_bf16 v[40:43], v[178:181], v[186:189], v[40:43]
	v_mfma_f32_16x16x32_bf16 v[28:31], v[170:173], v[194:197], v[28:31]
	v_mfma_f32_16x16x32_bf16 v[24:27], v[178:181], v[194:197], v[24:27]
	v_mfma_f32_16x16x32_bf16 v[12:15], v[170:173], v[202:205], v[12:15]
	v_mfma_f32_16x16x32_bf16 v[8:11], v[178:181], v[202:205], v[8:11]
	v_mfma_f32_16x16x32_bf16 v[4:7], v[170:173], v[210:213], v[4:7]
	v_mfma_f32_16x16x32_bf16 v[0:3], v[178:181], v[210:213], v[0:3]
	v_mfma_f32_16x16x32_bf16 v[44:47], v[174:177], v[190:193], v[44:47]
	v_mfma_f32_16x16x32_bf16 v[40:43], v[182:185], v[190:193], v[40:43]
	v_mfma_f32_16x16x32_bf16 v[28:31], v[174:177], v[198:201], v[28:31]
	v_mfma_f32_16x16x32_bf16 v[24:27], v[182:185], v[198:201], v[24:27]
	v_mfma_f32_16x16x32_bf16 v[12:15], v[174:177], v[206:209], v[12:15]
	v_mfma_f32_16x16x32_bf16 v[8:11], v[182:185], v[206:209], v[8:11]
	v_mfma_f32_16x16x32_bf16 v[4:7], v[174:177], v[214:217], v[4:7]
	v_mfma_f32_16x16x32_bf16 v[0:3], v[182:185], v[214:217], v[0:3]
	s_setprio 0
	s_barrier
	s_add_i32 s93, s93, 2
	s_add_u32 s68, s68, 0x100
	s_addc_u32 s69, s69, 0
	s_add_u32 s91, s91, 0x100
	s_addc_u32 s92, s92, 0
	s_cmp_gt_u32 s93, 29
	s_cbranch_scc0 .LBB0_119
	s_and_b64 vcc, exec, s[16:17]
	s_cbranch_vccz .LBB0_122
	s_barrier

; #define PG8_STAGE(bufoff, gbase, voff) do { _Pragma("unroll") for (int _i = 0; _i < 2; ++_i) \
;         __builtin_amdgcn_global_load_lds((const unsigned*)((const char*)(gbase) + (voff)[_i]), (PG8_LAS unsigned*)(lds + (bufoff) + ldsw + _i * 8192), 16, 0, 0); } while (0)
; #define PG8_LDA(dst, b, h) do { _Pragma("unroll") for (int m = 0; m < 4; ++m) _Pragma("unroll") for (int k = 0; k < 2; ++k) dst[m][k] = *(const PG8_LAS bf16x8*)(lds + PG8_SA(b, h) + aoff + m * 2048 + k * 1024); } while (0)
; #define PG8_LDB(dst, b, h) do { _Pragma("unroll") for (int n = 0; n < 2; ++n) _Pragma("unroll") for (int k = 0; k < 2; ++k) dst[n][k] = *(const PG8_LAS bf16x8*)(lds + PG8_SB(b, h) + boff + n * 2048 + k * 1024); } while (0)
; #define PG8_MMA(ai, bj, At, Bt) do { __builtin_amdgcn_s_setprio(1); _Pragma("unroll") for (int m = 0; m < 4; ++m) _Pragma("unroll") for (int n = 0; n < 2; ++n) _Pragma("unroll") for (int k = 0; k < 2; ++k) \
;         acc[ai][bj][m][n] = __builtin_amdgcn_mfma_f32_16x16x32_bf16(Bt[n][k], At[m][k], acc[ai][bj][m][n], 0, 0, 0); __builtin_amdgcn_s_setprio(0); } while (0)
; #define PG8_BAR __builtin_amdgcn_s_barrier()
; template <class Epi, class Sched, bool ALIGN_EPI = false, bool SP2 = false>
; __device__ __forceinline__ void gemm_phase(PG8_LAS unsigned char* lds, const Gemm g, const Sched& S, const Epi& E) {
;     ...
;             if constexpr (SP2) {
;             PG8_LDB(B0, 0, 0); PG8_LDB(B1, 0, 1); PG8_SCHED; PG8_LDA(At, 0, 0); PG8_STAGE(PG8_SA(1, 1), a1 + hstep, voffA);
;             PG8_WAIT_V(8); PG8_WAIT_L(0); PG8_BAR; PG8_MMA(0, 0, At, B0); PG8_MMA(0, 1, At, B1); PG8_BAR; PG8_SCHED;
;             PG8_LDA(At, 0, 1); PG8_STAGE(PG8_SB(0, 0), b2, voffB); PG8_STAGE(PG8_SB(0, 1), b2 + hstep, voffB); PG8_STAGE(PG8_SA(0, 0), a2, voffA);
;             PG8_WAIT_V(8); PG8_WAIT_L(0); PG8_BAR; PG8_MMA(1, 0, At, B0); PG8_MMA(1, 1, At, B1); PG8_BAR; PG8_SCHED;
;             PG8_LDB(B0, 1, 0); PG8_LDB(B1, 1, 1); PG8_SCHED; PG8_LDA(At, 1, 0); PG8_STAGE(PG8_SA(0, 1), a2 + hstep, voffA);
;             PG8_WAIT_V(8); PG8_WAIT_L(0); PG8_BAR; PG8_MMA(0, 0, At, B0); PG8_MMA(0, 1, At, B1); PG8_BAR; PG8_SCHED;
;             PG8_LDA(At, 1, 1); PG8_STAGE(PG8_SB(1, 0), b3, voffB); PG8_STAGE(PG8_SB(1, 1), b3 + hstep, voffB); PG8_STAGE(PG8_SA(1, 0), a3, voffA);
;             PG8_WAIT_V(8); PG8_WAIT_L(0); PG8_BAR; PG8_MMA(1, 0, At, B0); PG8_MMA(1, 1, At, B1); PG8_BAR; PG8_SCHED;
.LBB0_559:
	ds_read_b128 v[148:151], v145
	ds_read_b128 v[152:155], v145 offset:1024
	ds_read_b128 v[156:159], v145 offset:2048
	ds_read_b128 v[160:163], v145 offset:3072
	ds_read_b128 v[164:167], v146
	ds_read_b128 v[168:171], v146 offset:1024
	ds_read_b128 v[172:175], v146 offset:2048
	ds_read_b128 v[176:179], v146 offset:3072
	s_add_u32 s38, s36, 0x100
	s_addc_u32 s39, s37, 0
	s_cmp_eq_u32 s85, 28
	s_cselect_b32 s67, s25, s39
	s_cselect_b32 s66, s81, s38
	s_cselect_b32 s45, s23, s84
	s_cselect_b32 s44, s82, s83
	v_lshl_add_u64 v[140:141], s[36:37], 0, v[132:133]
	s_add_i32 m0, s68, 0xc000
	ds_read_b128 v[180:183], v147
	ds_read_b128 v[184:187], v147 offset:1024
	ds_read_b128 v[188:191], v147 offset:2048
	ds_read_b128 v[192:195], v147 offset:3072
	ds_read_b128 v[196:199], v147 offset:4096
	ds_read_b128 v[200:203], v147 offset:5120
	ds_read_b128 v[204:207], v147 offset:6144
	ds_read_b128 v[208:211], v147 offset:7168
	global_load_lds_dwordx4 v[140:141], off
	v_lshl_add_u64 v[140:141], s[36:37], 0, v[134:135]
	s_add_i32 m0, s68, 0xe000
	s_nop 0
	global_load_lds_dwordx4 v[140:141], off
	s_waitcnt vmcnt(8)
	s_waitcnt lgkmcnt(0)
	s_barrier
	s_setprio 1
	s_waitcnt lgkmcnt(0)
	v_mfma_f32_16x16x32_bf16 v[124:127], v[148:151], v[180:183], v[124:127]
	v_mfma_f32_16x16x32_bf16 v[120:123], v[156:159], v[180:183], v[120:123]
	v_mfma_f32_16x16x32_bf16 v[112:115], v[148:151], v[188:191], v[112:115]
	v_mfma_f32_16x16x32_bf16 v[108:111], v[156:159], v[188:191], v[108:111]
	v_mfma_f32_16x16x32_bf16 v[96:99], v[148:151], v[196:199], v[96:99]
	v_mfma_f32_16x16x32_bf16 v[92:95], v[156:159], v[196:199], v[92:95]
	v_mfma_f32_16x16x32_bf16 v[80:83], v[148:151], v[204:207], v[80:83]
	v_mfma_f32_16x16x32_bf16 v[76:79], v[156:159], v[204:207], v[76:79]
	v_mfma_f32_16x16x32_bf16 v[124:127], v[152:155], v[184:187], v[124:127]
	v_mfma_f32_16x16x32_bf16 v[120:123], v[160:163], v[184:187], v[120:123]
	v_mfma_f32_16x16x32_bf16 v[112:115], v[152:155], v[192:195], v[112:115]
	v_mfma_f32_16x16x32_bf16 v[108:111], v[160:163], v[192:195], v[108:111]
	v_mfma_f32_16x16x32_bf16 v[96:99], v[152:155], v[200:203], v[96:99]
	v_mfma_f32_16x16x32_bf16 v[92:95], v[160:163], v[200:203], v[92:95]
	v_mfma_f32_16x16x32_bf16 v[80:83], v[152:155], v[208:211], v[80:83]
	v_mfma_f32_16x16x32_bf16 v[76:79], v[160:163], v[208:211], v[76:79]
	v_mfma_f32_16x16x32_bf16 v[116:119], v[164:167], v[180:183], v[116:119]
	v_mfma_f32_16x16x32_bf16 v[104:107], v[172:175], v[180:183], v[104:107]
	v_mfma_f32_16x16x32_bf16 v[100:103], v[164:167], v[188:191], v[100:103]
	v_mfma_f32_16x16x32_bf16 v[88:91], v[172:175], v[188:191], v[88:91]
	v_mfma_f32_16x16x32_bf16 v[84:87], v[164:167], v[196:199], v[84:87]
	v_mfma_f32_16x16x32_bf16 v[72:75], v[172:175], v[196:199], v[72:75]
	v_mfma_f32_16x16x32_bf16 v[68:71], v[164:167], v[204:207], v[68:71]
	v_mfma_f32_16x16x32_bf16 v[64:67], v[172:175], v[204:207], v[64:67]
	v_mfma_f32_16x16x32_bf16 v[116:119], v[168:171], v[184:187], v[116:119]
	v_mfma_f32_16x16x32_bf16 v[104:107], v[176:179], v[184:187], v[104:107]
	v_mfma_f32_16x16x32_bf16 v[100:103], v[168:171], v[192:195], v[100:103]
	v_mfma_f32_16x16x32_bf16 v[88:91], v[176:179], v[192:195], v[88:91]
	v_mfma_f32_16x16x32_bf16 v[84:87], v[168:171], v[200:203], v[84:87]
	v_mfma_f32_16x16x32_bf16 v[72:75], v[176:179], v[200:203], v[72:75]
	v_mfma_f32_16x16x32_bf16 v[68:71], v[168:171], v[208:211], v[68:71]
	v_mfma_f32_16x16x32_bf16 v[64:67], v[176:179], v[208:211], v[64:67]
	s_setprio 0
	s_barrier
	s_add_i32 s36, s79, s3
	v_lshl_add_u64 v[140:141], s[44:45], 0, v[130:131]
	s_mov_b32 m0, s36
	ds_read_b128 v[180:183], v147 offset:16384
	ds_read_b128 v[184:187], v147 offset:17408
	ds_read_b128 v[188:191], v147 offset:18432
	ds_read_b128 v[192:195], v147 offset:19456
	ds_read_b128 v[196:199], v147 offset:20480
	ds_read_b128 v[200:203], v147 offset:21504
	ds_read_b128 v[204:207], v147 offset:22528
	ds_read_b128 v[208:211], v147 offset:23552
	global_load_lds_dwordx4 v[140:141], off
	s_add_i32 m0, s36, 0x2000
	s_add_u32 s36, s44, 0x80000
	v_lshl_add_u64 v[212:213], s[44:45], 0, v[128:129]
	s_addc_u32 s37, s45, 0
	s_add_i32 s86, s80, s3
	global_load_lds_dwordx4 v[212:213], off
	v_lshl_add_u64 v[214:215], s[36:37], 0, v[130:131]
	s_mov_b32 m0, s86
	v_lshl_add_u64 v[216:217], s[66:67], 0, v[128:129]
	global_load_lds_dwordx4 v[214:215], off
	v_lshl_add_u64 v[214:215], s[36:37], 0, v[128:129]
	s_add_i32 m0, s86, 0x2000
	s_nop 0
	global_load_lds_dwordx4 v[214:215], off
	v_lshl_add_u64 v[214:215], s[66:67], 0, v[130:131]
	s_mov_b32 m0, s68
	s_nop 0
	global_load_lds_dwordx4 v[214:215], off
	s_mov_b32 m0, s69
	s_nop 0
	global_load_lds_dwordx4 v[216:217], off
	s_waitcnt vmcnt(8)
	s_waitcnt lgkmcnt(0)
	s_barrier
; #define PG8_STAGE(bufoff, gbase, voff) do { _Pragma("unroll") for (int _i = 0; _i < 2; ++_i) \
;         __builtin_amdgcn_global_load_lds((const unsigned*)((const char*)(gbase) + (voff)[_i]), (PG8_LAS unsigned*)(lds + (bufoff) + ldsw + _i * 8192), 16, 0, 0); } while (0)
; #define PG8_LDA(dst, b, h) do { _Pragma("unroll") for (int m = 0; m < 4; ++m) _Pragma("unroll") for (int k = 0; k < 2; ++k) dst[m][k] = *(const PG8_LAS bf16x8*)(lds + PG8_SA(b, h) + aoff + m * 2048 + k * 1024); } while (0)
; #define PG8_LDB(dst, b, h) do { _Pragma("unroll") for (int n = 0; n < 2; ++n) _Pragma("unroll") for (int k = 0; k < 2; ++k) dst[n][k] = *(const PG8_LAS bf16x8*)(lds + PG8_SB(b, h) + boff + n * 2048 + k * 1024); } while (0)
; #define PG8_MMA(ai, bj, At, Bt) do { __builtin_amdgcn_s_setprio(1); _Pragma("unroll") for (int m = 0; m < 4; ++m) _Pragma("unroll") for (int n = 0; n < 2; ++n) _Pragma("unroll") for (int k = 0; k < 2; ++k) \
;         acc[ai][bj][m][n] = __builtin_amdgcn_mfma_f32_16x16x32_bf16(Bt[n][k], At[m][k], acc[ai][bj][m][n], 0, 0, 0); __builtin_amdgcn_s_setprio(0); } while (0)
; #define PG8_BAR __builtin_amdgcn_s_barrier()
; template <class Epi, class Sched, bool ALIGN_EPI = false, bool SP2 = false>
; __device__ __forceinline__ void gemm_phase(PG8_LAS unsigned char* lds, const Gemm g, const Sched& S, const Epi& E) {
;     ...
;             if constexpr (SP2) {
;             PG8_LDB(B0, 0, 0); PG8_LDB(B1, 0, 1); PG8_SCHED; PG8_LDA(At, 0, 0); PG8_STAGE(PG8_SA(1, 1), a1 + hstep, voffA);
;             PG8_WAIT_V(8); PG8_WAIT_L(0); PG8_BAR; PG8_MMA(0, 0, At, B0); PG8_MMA(0, 1, At, B1); PG8_BAR; PG8_SCHED;
;             PG8_LDA(At, 0, 1); PG8_STAGE(PG8_SB(0, 0), b2, voffB); PG8_STAGE(PG8_SB(0, 1), b2 + hstep, voffB); PG8_STAGE(PG8_SA(0, 0), a2, voffA);
;             PG8_WAIT_V(8); PG8_WAIT_L(0); PG8_BAR; PG8_MMA(1, 0, At, B0); PG8_MMA(1, 1, At, B1); PG8_BAR; PG8_SCHED;
;             PG8_LDB(B0, 1, 0); PG8_LDB(B1, 1, 1); PG8_SCHED; PG8_LDA(At, 1, 0); PG8_STAGE(PG8_SA(0, 1), a2 + hstep, voffA);
;             PG8_WAIT_V(8); PG8_WAIT_L(0); PG8_BAR; PG8_MMA(0, 0, At, B0); PG8_MMA(0, 1, At, B1); PG8_BAR; PG8_SCHED;
;             PG8_LDA(At, 1, 1); PG8_STAGE(PG8_SB(1, 0), b3, voffB); PG8_STAGE(PG8_SB(1, 1), b3 + hstep, voffB); PG8_STAGE(PG8_SA(1, 0), a3, voffA);
;             PG8_WAIT_V(8); PG8_WAIT_L(0); PG8_BAR; PG8_MMA(1, 0, At, B0); PG8_MMA(1, 1, At, B1); PG8_BAR; PG8_SCHED;
	s_setprio 1
	s_waitcnt lgkmcnt(0)
	v_mfma_f32_16x16x32_bf16 v[60:63], v[148:151], v[180:183], v[60:63]
	v_mfma_f32_16x16x32_bf16 v[56:59], v[156:159], v[180:183], v[56:59]
	v_mfma_f32_16x16x32_bf16 v[48:51], v[148:151], v[188:191], v[48:51]
	v_mfma_f32_16x16x32_bf16 v[44:47], v[156:159], v[188:191], v[44:47]
	v_mfma_f32_16x16x32_bf16 v[32:35], v[148:151], v[196:199], v[32:35]
	v_mfma_f32_16x16x32_bf16 v[28:31], v[156:159], v[196:199], v[28:31]
	v_mfma_f32_16x16x32_bf16 v[16:19], v[148:151], v[204:207], v[16:19]
	v_mfma_f32_16x16x32_bf16 v[12:15], v[156:159], v[204:207], v[12:15]
	v_mfma_f32_16x16x32_bf16 v[60:63], v[152:155], v[184:187], v[60:63]
	v_mfma_f32_16x16x32_bf16 v[56:59], v[160:163], v[184:187], v[56:59]
	v_mfma_f32_16x16x32_bf16 v[48:51], v[152:155], v[192:195], v[48:51]
	v_mfma_f32_16x16x32_bf16 v[44:47], v[160:163], v[192:195], v[44:47]
	v_mfma_f32_16x16x32_bf16 v[32:35], v[152:155], v[200:203], v[32:35]
	v_mfma_f32_16x16x32_bf16 v[28:31], v[160:163], v[200:203], v[28:31]
	v_mfma_f32_16x16x32_bf16 v[16:19], v[152:155], v[208:211], v[16:19]
	v_mfma_f32_16x16x32_bf16 v[12:15], v[160:163], v[208:211], v[12:15]
	v_mfma_f32_16x16x32_bf16 v[52:55], v[164:167], v[180:183], v[52:55]
	v_mfma_f32_16x16x32_bf16 v[40:43], v[172:175], v[180:183], v[40:43]
	v_mfma_f32_16x16x32_bf16 v[36:39], v[164:167], v[188:191], v[36:39]
	v_mfma_f32_16x16x32_bf16 v[24:27], v[172:175], v[188:191], v[24:27]
	v_mfma_f32_16x16x32_bf16 v[20:23], v[164:167], v[196:199], v[20:23]
	v_mfma_f32_16x16x32_bf16 v[8:11], v[172:175], v[196:199], v[8:11]
	v_mfma_f32_16x16x32_bf16 v[4:7], v[164:167], v[204:207], v[4:7]
	v_mfma_f32_16x16x32_bf16 v[0:3], v[172:175], v[204:207], v[0:3]
	v_mfma_f32_16x16x32_bf16 v[52:55], v[168:171], v[184:187], v[52:55]
	v_mfma_f32_16x16x32_bf16 v[40:43], v[176:179], v[184:187], v[40:43]
	v_mfma_f32_16x16x32_bf16 v[36:39], v[168:171], v[192:195], v[36:39]
	v_mfma_f32_16x16x32_bf16 v[24:27], v[176:179], v[192:195], v[24:27]
	v_mfma_f32_16x16x32_bf16 v[20:23], v[168:171], v[200:203], v[20:23]
	v_mfma_f32_16x16x32_bf16 v[8:11], v[176:179], v[200:203], v[8:11]
	v_mfma_f32_16x16x32_bf16 v[4:7], v[168:171], v[208:211], v[4:7]
	v_mfma_f32_16x16x32_bf16 v[0:3], v[176:179], v[208:211], v[0:3]
	s_setprio 0
	s_barrier
	s_add_i32 s86, 0, 0x18000
	s_add_i32 s87, 0, 0x1c000
	v_add_u32_e32 v160, s86, v143
	v_add_u32_e32 v176, s87, v143
	ds_read_b128 v[148:151], v160
	ds_read_b128 v[152:155], v160 offset:1024
	ds_read_b128 v[156:159], v160 offset:2048
	ds_read_b128 v[160:163], v160 offset:3072
	ds_read_b128 v[164:167], v176
	ds_read_b128 v[168:171], v176 offset:1024
	ds_read_b128 v[172:175], v176 offset:2048
	ds_read_b128 v[176:179], v176 offset:3072
	s_add_u32 s36, s66, 0x80000
	s_addc_u32 s37, s67, 0
	s_mov_b32 m0, s70
	v_lshl_add_u64 v[218:219], s[36:37], 0, v[130:131]
	ds_read_b128 v[180:183], v147 offset:32768
	ds_read_b128 v[184:187], v147 offset:33792
	ds_read_b128 v[188:191], v147 offset:34816
	ds_read_b128 v[192:195], v147 offset:35840
	ds_read_b128 v[196:199], v147 offset:36864
	ds_read_b128 v[200:203], v147 offset:37888
	ds_read_b128 v[204:207], v147 offset:38912
	ds_read_b128 v[208:211], v147 offset:39936
	global_load_lds_dwordx4 v[218:219], off
	v_lshl_add_u64 v[218:219], s[36:37], 0, v[128:129]
	s_mov_b32 m0, s71
	s_nop 0
	global_load_lds_dwordx4 v[218:219], off
	s_waitcnt vmcnt(8)
	s_waitcnt lgkmcnt(0)
	s_barrier
	s_setprio 1
	s_waitcnt lgkmcnt(0)
	v_mfma_f32_16x16x32_bf16 v[124:127], v[148:151], v[180:183], v[124:127]
	v_mfma_f32_16x16x32_bf16 v[120:123], v[156:159], v[180:183], v[120:123]
	v_mfma_f32_16x16x32_bf16 v[112:115], v[148:151], v[188:191], v[112:115]
	v_mfma_f32_16x16x32_bf16 v[108:111], v[156:159], v[188:191], v[108:111]
	v_mfma_f32_16x16x32_bf16 v[96:99], v[148:151], v[196:199], v[96:99]
	v_mfma_f32_16x16x32_bf16 v[92:95], v[156:159], v[196:199], v[92:95]
	v_mfma_f32_16x16x32_bf16 v[80:83], v[148:151], v[204:207], v[80:83]
	v_mfma_f32_16x16x32_bf16 v[76:79], v[156:159], v[204:207], v[76:79]
	v_mfma_f32_16x16x32_bf16 v[124:127], v[152:155], v[184:187], v[124:127]
	v_mfma_f32_16x16x32_bf16 v[120:123], v[160:163], v[184:187], v[120:123]
	v_mfma_f32_16x16x32_bf16 v[112:115], v[152:155], v[192:195], v[112:115]
	v_mfma_f32_16x16x32_bf16 v[108:111], v[160:163], v[192:195], v[108:111]
	v_mfma_f32_16x16x32_bf16 v[96:99], v[152:155], v[200:203], v[96:99]
	v_mfma_f32_16x16x32_bf16 v[92:95], v[160:163], v[200:203], v[92:95]
	v_mfma_f32_16x16x32_bf16 v[80:83], v[152:155], v[208:211], v[80:83]
	v_mfma_f32_16x16x32_bf16 v[76:79], v[160:163], v[208:211], v[76:79]
	v_mfma_f32_16x16x32_bf16 v[116:119], v[164:167], v[180:183], v[116:119]
	v_mfma_f32_16x16x32_bf16 v[104:107], v[172:175], v[180:183], v[104:107]
	v_mfma_f32_16x16x32_bf16 v[100:103], v[164:167], v[188:191], v[100:103]
	v_mfma_f32_16x16x32_bf16 v[88:91], v[172:175], v[188:191], v[88:91]
	v_mfma_f32_16x16x32_bf16 v[84:87], v[164:167], v[196:199], v[84:87]
	v_mfma_f32_16x16x32_bf16 v[72:75], v[172:175], v[196:199], v[72:75]
	v_mfma_f32_16x16x32_bf16 v[68:71], v[164:167], v[204:207], v[68:71]
	v_mfma_f32_16x16x32_bf16 v[64:67], v[172:175], v[204:207], v[64:67]
	v_mfma_f32_16x16x32_bf16 v[116:119], v[168:171], v[184:187], v[116:119]
	v_mfma_f32_16x16x32_bf16 v[104:107], v[176:179], v[184:187], v[104:107]
	v_mfma_f32_16x16x32_bf16 v[100:103], v[168:171], v[192:195], v[100:103]
	v_mfma_f32_16x16x32_bf16 v[88:91], v[176:179], v[192:195], v[88:91]
	v_mfma_f32_16x16x32_bf16 v[84:87], v[168:171], v[200:203], v[84:87]
	v_mfma_f32_16x16x32_bf16 v[72:75], v[176:179], v[200:203], v[72:75]
	v_mfma_f32_16x16x32_bf16 v[68:71], v[168:171], v[208:211], v[68:71]
	v_mfma_f32_16x16x32_bf16 v[64:67], v[176:179], v[208:211], v[64:67]
	s_setprio 0
	s_barrier
; #define PG8_STAGE(bufoff, gbase, voff) do { _Pragma("unroll") for (int _i = 0; _i < 2; ++_i) \
;         __builtin_amdgcn_global_load_lds((const unsigned*)((const char*)(gbase) + (voff)[_i]), (PG8_LAS unsigned*)(lds + (bufoff) + ldsw + _i * 8192), 16, 0, 0); } while (0)
; #define PG8_LDA(dst, b, h) do { _Pragma("unroll") for (int m = 0; m < 4; ++m) _Pragma("unroll") for (int k = 0; k < 2; ++k) dst[m][k] = *(const PG8_LAS bf16x8*)(lds + PG8_SA(b, h) + aoff + m * 2048 + k * 1024); } while (0)
; #define PG8_LDB(dst, b, h) do { _Pragma("unroll") for (int n = 0; n < 2; ++n) _Pragma("unroll") for (int k = 0; k < 2; ++k) dst[n][k] = *(const PG8_LAS bf16x8*)(lds + PG8_SB(b, h) + boff + n * 2048 + k * 1024); } while (0)
; #define PG8_MMA(ai, bj, At, Bt) do { __builtin_amdgcn_s_setprio(1); _Pragma("unroll") for (int m = 0; m < 4; ++m) _Pragma("unroll") for (int n = 0; n < 2; ++n) _Pragma("unroll") for (int k = 0; k < 2; ++k) \
;         acc[ai][bj][m][n] = __builtin_amdgcn_mfma_f32_16x16x32_bf16(Bt[n][k], At[m][k], acc[ai][bj][m][n], 0, 0, 0); __builtin_amdgcn_s_setprio(0); } while (0)
; #define PG8_BAR __builtin_amdgcn_s_barrier()
; template <class Epi, class Sched, bool ALIGN_EPI = false, bool SP2 = false>
; __device__ __forceinline__ void gemm_phase(PG8_LAS unsigned char* lds, const Gemm g, const Sched& S, const Epi& E) {
;     ...
;             if constexpr (SP2) {
;             PG8_LDB(B0, 0, 0); PG8_LDB(B1, 0, 1); PG8_SCHED; PG8_LDA(At, 0, 0); PG8_STAGE(PG8_SA(1, 1), a1 + hstep, voffA);
;             PG8_WAIT_V(8); PG8_WAIT_L(0); PG8_BAR; PG8_MMA(0, 0, At, B0); PG8_MMA(0, 1, At, B1); PG8_BAR; PG8_SCHED;
;             PG8_LDA(At, 0, 1); PG8_STAGE(PG8_SB(0, 0), b2, voffB); PG8_STAGE(PG8_SB(0, 1), b2 + hstep, voffB); PG8_STAGE(PG8_SA(0, 0), a2, voffA);
;             PG8_WAIT_V(8); PG8_WAIT_L(0); PG8_BAR; PG8_MMA(1, 0, At, B0); PG8_MMA(1, 1, At, B1); PG8_BAR; PG8_SCHED;
;             PG8_LDB(B0, 1, 0); PG8_LDB(B1, 1, 1); PG8_SCHED; PG8_LDA(At, 1, 0); PG8_STAGE(PG8_SA(0, 1), a2 + hstep, voffA);
;             PG8_WAIT_V(8); PG8_WAIT_L(0); PG8_BAR; PG8_MMA(0, 0, At, B0); PG8_MMA(0, 1, At, B1); PG8_BAR; PG8_SCHED;
;             PG8_LDA(At, 1, 1); PG8_STAGE(PG8_SB(1, 0), b3, voffB); PG8_STAGE(PG8_SB(1, 1), b3 + hstep, voffB); PG8_STAGE(PG8_SA(1, 0), a3, voffA);
;             PG8_WAIT_V(8); PG8_WAIT_L(0); PG8_BAR; PG8_MMA(1, 0, At, B0); PG8_MMA(1, 1, At, B1); PG8_BAR; PG8_SCHED;
	s_add_i32 s36, s86, s3
	v_lshl_add_u64 v[140:141], v[140:141], 0, s[8:9]
	s_mov_b32 m0, s36
	ds_read_b128 v[180:183], v147 offset:49152
	ds_read_b128 v[184:187], v147 offset:50176
	ds_read_b128 v[188:191], v147 offset:51200
	ds_read_b128 v[192:195], v147 offset:52224
	ds_read_b128 v[196:199], v147 offset:53248
	ds_read_b128 v[200:203], v147 offset:54272
	ds_read_b128 v[204:207], v147 offset:55296
	ds_read_b128 v[208:211], v147 offset:56320
	global_load_lds_dwordx4 v[140:141], off
	s_add_i32 m0, s36, 0x2000
	s_add_u32 s36, s44, 0x80080
	v_lshl_add_u64 v[140:141], v[212:213], 0, s[8:9]
	s_addc_u32 s37, s45, 0
	s_add_i32 s44, s87, s3
	global_load_lds_dwordx4 v[140:141], off
	v_lshl_add_u64 v[140:141], s[36:37], 0, v[130:131]
	s_mov_b32 m0, s44
	s_nop 0
	global_load_lds_dwordx4 v[140:141], off
	v_lshl_add_u64 v[140:141], s[36:37], 0, v[128:129]
	s_add_i32 m0, s44, 0x2000
	s_nop 0
	global_load_lds_dwordx4 v[140:141], off
	v_lshl_add_u64 v[140:141], v[214:215], 0, s[8:9]
	s_mov_b32 m0, s75
	s_nop 0
	global_load_lds_dwordx4 v[140:141], off
	v_lshl_add_u64 v[140:141], v[216:217], 0, s[8:9]
	s_mov_b32 m0, s76
	s_nop 0
	global_load_lds_dwordx4 v[140:141], off
	s_waitcnt vmcnt(8)
	s_waitcnt lgkmcnt(0)
	s_barrier
	s_setprio 1
	s_waitcnt lgkmcnt(0)
	v_mfma_f32_16x16x32_bf16 v[60:63], v[148:151], v[180:183], v[60:63]
	v_mfma_f32_16x16x32_bf16 v[56:59], v[156:159], v[180:183], v[56:59]
	v_mfma_f32_16x16x32_bf16 v[48:51], v[148:151], v[188:191], v[48:51]
	v_mfma_f32_16x16x32_bf16 v[44:47], v[156:159], v[188:191], v[44:47]
	v_mfma_f32_16x16x32_bf16 v[32:35], v[148:151], v[196:199], v[32:35]
	v_mfma_f32_16x16x32_bf16 v[28:31], v[156:159], v[196:199], v[28:31]
	v_mfma_f32_16x16x32_bf16 v[16:19], v[148:151], v[204:207], v[16:19]
	v_mfma_f32_16x16x32_bf16 v[12:15], v[156:159], v[204:207], v[12:15]
	v_mfma_f32_16x16x32_bf16 v[60:63], v[152:155], v[184:187], v[60:63]
	v_mfma_f32_16x16x32_bf16 v[56:59], v[160:163], v[184:187], v[56:59]
	v_mfma_f32_16x16x32_bf16 v[48:51], v[152:155], v[192:195], v[48:51]
	v_mfma_f32_16x16x32_bf16 v[44:47], v[160:163], v[192:195], v[44:47]
	v_mfma_f32_16x16x32_bf16 v[32:35], v[152:155], v[200:203], v[32:35]
	v_mfma_f32_16x16x32_bf16 v[28:31], v[160:163], v[200:203], v[28:31]
	v_mfma_f32_16x16x32_bf16 v[16:19], v[152:155], v[208:211], v[16:19]
	v_mfma_f32_16x16x32_bf16 v[12:15], v[160:163], v[208:211], v[12:15]
	v_mfma_f32_16x16x32_bf16 v[52:55], v[164:167], v[180:183], v[52:55]
	v_mfma_f32_16x16x32_bf16 v[40:43], v[172:175], v[180:183], v[40:43]
	v_mfma_f32_16x16x32_bf16 v[36:39], v[164:167], v[188:191], v[36:39]
	v_mfma_f32_16x16x32_bf16 v[24:27], v[172:175], v[188:191], v[24:27]
	v_mfma_f32_16x16x32_bf16 v[20:23], v[164:167], v[196:199], v[20:23]
	v_mfma_f32_16x16x32_bf16 v[8:11], v[172:175], v[196:199], v[8:11]
	v_mfma_f32_16x16x32_bf16 v[4:7], v[164:167], v[204:207], v[4:7]
	v_mfma_f32_16x16x32_bf16 v[0:3], v[172:175], v[204:207], v[0:3]
	v_mfma_f32_16x16x32_bf16 v[52:55], v[168:171], v[184:187], v[52:55]
	v_mfma_f32_16x16x32_bf16 v[40:43], v[176:179], v[184:187], v[40:43]
	v_mfma_f32_16x16x32_bf16 v[36:39], v[168:171], v[192:195], v[36:39]
	v_mfma_f32_16x16x32_bf16 v[24:27], v[176:179], v[192:195], v[24:27]
	v_mfma_f32_16x16x32_bf16 v[20:23], v[168:171], v[200:203], v[20:23]
	v_mfma_f32_16x16x32_bf16 v[8:11], v[176:179], v[200:203], v[8:11]
	v_mfma_f32_16x16x32_bf16 v[4:7], v[168:171], v[208:211], v[4:7]
	v_mfma_f32_16x16x32_bf16 v[0:3], v[176:179], v[208:211], v[0:3]
	s_setprio 0
	s_barrier
	s_add_i32 s85, s85, 2
	s_add_u32 s83, s83, 0x100
	s_addc_u32 s84, s84, 0
	s_cmp_gt_u32 s85, 29
	s_mov_b64 s[36:37], s[38:39]
	s_cbranch_scc0 .LBB0_559
	s_and_b64 vcc, exec, s[10:11]
	s_cbranch_vccz .LBB0_562
	s_barrier

; #define PG8_STAGE(bufoff, gbase, voff) do { _Pragma("unroll") for (int _i = 0; _i < 2; ++_i) \
;         __builtin_amdgcn_global_load_lds((const unsigned*)((const char*)(gbase) + (voff)[_i]), (PG8_LAS unsigned*)(lds + (bufoff) + ldsw + _i * 8192), 16, 0, 0); } while (0)
; #define PG8_LDA(dst, b, h) do { _Pragma("unroll") for (int m = 0; m < 4; ++m) _Pragma("unroll") for (int k = 0; k < 2; ++k) dst[m][k] = *(const PG8_LAS bf16x8*)(lds + PG8_SA(b, h) + aoff + m * 2048 + k * 1024); } while (0)
; #define PG8_LDB(dst, b, h) do { _Pragma("unroll") for (int n = 0; n < 2; ++n) _Pragma("unroll") for (int k = 0; k < 2; ++k) dst[n][k] = *(const PG8_LAS bf16x8*)(lds + PG8_SB(b, h) + boff + n * 2048 + k * 1024); } while (0)
; #define PG8_MMA(ai, bj, At, Bt) do { __builtin_amdgcn_s_setprio(1); _Pragma("unroll") for (int m = 0; m < 4; ++m) _Pragma("unroll") for (int n = 0; n < 2; ++n) _Pragma("unroll") for (int k = 0; k < 2; ++k) \
;         acc[ai][bj][m][n] = __builtin_amdgcn_mfma_f32_16x16x32_bf16(Bt[n][k], At[m][k], acc[ai][bj][m][n], 0, 0, 0); __builtin_amdgcn_s_setprio(0); } while (0)
; #define PG8_BAR __builtin_amdgcn_s_barrier()
; template <class Epi, class Sched, bool ALIGN_EPI = false, bool SP2 = false>
; __device__ __forceinline__ void gemm_phase(PG8_LAS unsigned char* lds, const Gemm g, const Sched& S, const Epi& E) {
;     ...
;             if constexpr (SP2) {
;             PG8_LDB(B0, 0, 0); PG8_LDB(B1, 0, 1); PG8_SCHED; PG8_LDA(At, 0, 0); PG8_STAGE(PG8_SA(1, 1), a1 + hstep, voffA);
;             PG8_WAIT_V(8); PG8_WAIT_L(0); PG8_BAR; PG8_MMA(0, 0, At, B0); PG8_MMA(0, 1, At, B1); PG8_BAR; PG8_SCHED;
;             PG8_LDA(At, 0, 1); PG8_STAGE(PG8_SB(0, 0), b2, voffB); PG8_STAGE(PG8_SB(0, 1), b2 + hstep, voffB); PG8_STAGE(PG8_SA(0, 0), a2, voffA);
;             PG8_WAIT_V(8); PG8_WAIT_L(0); PG8_BAR; PG8_MMA(1, 0, At, B0); PG8_MMA(1, 1, At, B1); PG8_BAR; PG8_SCHED;
;             PG8_LDB(B0, 1, 0); PG8_LDB(B1, 1, 1); PG8_SCHED; PG8_LDA(At, 1, 0); PG8_STAGE(PG8_SA(0, 1), a2 + hstep, voffA);
;             PG8_WAIT_V(8); PG8_WAIT_L(0); PG8_BAR; PG8_MMA(0, 0, At, B0); PG8_MMA(0, 1, At, B1); PG8_BAR; PG8_SCHED;
;             PG8_LDA(At, 1, 1); PG8_STAGE(PG8_SB(1, 0), b3, voffB); PG8_STAGE(PG8_SB(1, 1), b3 + hstep, voffB); PG8_STAGE(PG8_SA(1, 0), a3, voffA);
;             PG8_WAIT_V(8); PG8_WAIT_L(0); PG8_BAR; PG8_MMA(1, 0, At, B0); PG8_MMA(1, 1, At, B1); PG8_BAR; PG8_SCHED;
.LBB0_704:
	s_add_u32 s10, s8, 0xfff80080
	s_addc_u32 s11, s9, -1
	s_add_i32 s35, 0, 0x10000
	s_cmp_eq_u32 s34, 28
	s_cselect_b32 s13, s31, s11
	s_cselect_b32 s12, s74, s10
	v_add_u32_e32 v142, s35, v146
	s_cselect_b32 s11, s39, vcc_hi
	s_cselect_b32 s10, s89, vcc_lo
	s_add_i32 s54, 0, 0x14000
	ds_read_b128 v[150:153], v142
	ds_read_b128 v[154:157], v142 offset:1024
	ds_read_b128 v[158:161], v142 offset:2048
	ds_read_b128 v[162:165], v142 offset:3072
	v_add_u32_e32 v142, s54, v146
	ds_read_b128 v[166:169], v142
	ds_read_b128 v[170:173], v142 offset:1024
	ds_read_b128 v[174:177], v142 offset:2048
	ds_read_b128 v[178:181], v142 offset:3072
	v_lshl_add_u64 v[142:143], s[8:9], 0, v[136:137]
	s_add_i32 m0, s25, 0xc000
	ds_read_b128 v[182:185], v148
	ds_read_b128 v[186:189], v148 offset:1024
	ds_read_b128 v[190:193], v148 offset:2048
	ds_read_b128 v[194:197], v148 offset:3072
	ds_read_b128 v[198:201], v148 offset:4096
	ds_read_b128 v[202:205], v148 offset:5120
	ds_read_b128 v[206:209], v148 offset:6144
	ds_read_b128 v[210:213], v148 offset:7168
	global_load_lds_dwordx4 v[142:143], off
	v_lshl_add_u64 v[142:143], s[8:9], 0, v[138:139]
	s_add_i32 m0, s25, 0xe000
	s_nop 0
	global_load_lds_dwordx4 v[142:143], off
	s_waitcnt vmcnt(8)
	s_waitcnt lgkmcnt(0)
	s_barrier
	s_setprio 1
	s_waitcnt lgkmcnt(0)
	v_mfma_f32_16x16x32_bf16 v[124:127], v[150:153], v[182:185], v[124:127]
	v_mfma_f32_16x16x32_bf16 v[120:123], v[158:161], v[182:185], v[120:123]
	v_mfma_f32_16x16x32_bf16 v[108:111], v[150:153], v[190:193], v[108:111]
	v_mfma_f32_16x16x32_bf16 v[104:107], v[158:161], v[190:193], v[104:107]
	v_mfma_f32_16x16x32_bf16 v[92:95], v[150:153], v[198:201], v[92:95]
	v_mfma_f32_16x16x32_bf16 v[88:91], v[158:161], v[198:201], v[88:91]
	v_mfma_f32_16x16x32_bf16 v[76:79], v[150:153], v[206:209], v[76:79]
	v_mfma_f32_16x16x32_bf16 v[72:75], v[158:161], v[206:209], v[72:75]
	v_mfma_f32_16x16x32_bf16 v[124:127], v[154:157], v[186:189], v[124:127]
	v_mfma_f32_16x16x32_bf16 v[120:123], v[162:165], v[186:189], v[120:123]
	v_mfma_f32_16x16x32_bf16 v[108:111], v[154:157], v[194:197], v[108:111]
	v_mfma_f32_16x16x32_bf16 v[104:107], v[162:165], v[194:197], v[104:107]
	v_mfma_f32_16x16x32_bf16 v[92:95], v[154:157], v[202:205], v[92:95]
	v_mfma_f32_16x16x32_bf16 v[88:91], v[162:165], v[202:205], v[88:91]
	v_mfma_f32_16x16x32_bf16 v[76:79], v[154:157], v[210:213], v[76:79]
	v_mfma_f32_16x16x32_bf16 v[72:75], v[162:165], v[210:213], v[72:75]
	v_mfma_f32_16x16x32_bf16 v[116:119], v[166:169], v[182:185], v[116:119]
	v_mfma_f32_16x16x32_bf16 v[112:115], v[174:177], v[182:185], v[112:115]
	v_mfma_f32_16x16x32_bf16 v[100:103], v[166:169], v[190:193], v[100:103]
	v_mfma_f32_16x16x32_bf16 v[96:99], v[174:177], v[190:193], v[96:99]
	v_mfma_f32_16x16x32_bf16 v[84:87], v[166:169], v[198:201], v[84:87]
	v_mfma_f32_16x16x32_bf16 v[80:83], v[174:177], v[198:201], v[80:83]
	v_mfma_f32_16x16x32_bf16 v[68:71], v[166:169], v[206:209], v[68:71]
	v_mfma_f32_16x16x32_bf16 v[64:67], v[174:177], v[206:209], v[64:67]
	v_mfma_f32_16x16x32_bf16 v[116:119], v[170:173], v[186:189], v[116:119]
	v_mfma_f32_16x16x32_bf16 v[112:115], v[178:181], v[186:189], v[112:115]
	v_mfma_f32_16x16x32_bf16 v[100:103], v[170:173], v[194:197], v[100:103]
	v_mfma_f32_16x16x32_bf16 v[96:99], v[178:181], v[194:197], v[96:99]
	v_mfma_f32_16x16x32_bf16 v[84:87], v[170:173], v[202:205], v[84:87]
	v_mfma_f32_16x16x32_bf16 v[80:83], v[178:181], v[202:205], v[80:83]
	v_mfma_f32_16x16x32_bf16 v[68:71], v[170:173], v[210:213], v[68:71]
	v_mfma_f32_16x16x32_bf16 v[64:67], v[178:181], v[210:213], v[64:67]
	s_setprio 0
	s_barrier
	s_add_i32 s35, s35, s24
	v_lshl_add_u64 v[142:143], s[10:11], 0, v[128:129]
	s_mov_b32 m0, s35
	ds_read_b128 v[182:185], v148 offset:16384
	ds_read_b128 v[186:189], v148 offset:17408
	ds_read_b128 v[190:193], v148 offset:18432
	ds_read_b128 v[194:197], v148 offset:19456
	ds_read_b128 v[198:201], v148 offset:20480
	ds_read_b128 v[202:205], v148 offset:21504
	ds_read_b128 v[206:209], v148 offset:22528
	ds_read_b128 v[210:213], v148 offset:23552
	global_load_lds_dwordx4 v[142:143], off
	s_add_i32 m0, s35, 0x2000
	s_add_u32 s80, s10, 0x80000
	v_lshl_add_u64 v[214:215], s[10:11], 0, v[134:135]
	s_addc_u32 s81, s11, 0
	s_add_i32 s35, s54, s24
	global_load_lds_dwordx4 v[214:215], off
	v_lshl_add_u64 v[216:217], s[80:81], 0, v[128:129]
	s_mov_b32 m0, s35
	v_lshl_add_u64 v[218:219], s[12:13], 0, v[132:133]
	global_load_lds_dwordx4 v[216:217], off
	v_lshl_add_u64 v[216:217], s[80:81], 0, v[134:135]
	s_add_i32 m0, s35, 0x2000
	s_nop 0
	global_load_lds_dwordx4 v[216:217], off
	v_lshl_add_u64 v[216:217], s[12:13], 0, v[130:131]
	s_mov_b32 m0, s25
	s_nop 0
	global_load_lds_dwordx4 v[216:217], off
	s_mov_b32 m0, s26
	s_nop 0
	global_load_lds_dwordx4 v[218:219], off
	s_waitcnt vmcnt(8)
	s_waitcnt lgkmcnt(0)
	s_barrier
; #define PG8_STAGE(bufoff, gbase, voff) do { _Pragma("unroll") for (int _i = 0; _i < 2; ++_i) \
;         __builtin_amdgcn_global_load_lds((const unsigned*)((const char*)(gbase) + (voff)[_i]), (PG8_LAS unsigned*)(lds + (bufoff) + ldsw + _i * 8192), 16, 0, 0); } while (0)
; #define PG8_LDA(dst, b, h) do { _Pragma("unroll") for (int m = 0; m < 4; ++m) _Pragma("unroll") for (int k = 0; k < 2; ++k) dst[m][k] = *(const PG8_LAS bf16x8*)(lds + PG8_SA(b, h) + aoff + m * 2048 + k * 1024); } while (0)
; #define PG8_LDB(dst, b, h) do { _Pragma("unroll") for (int n = 0; n < 2; ++n) _Pragma("unroll") for (int k = 0; k < 2; ++k) dst[n][k] = *(const PG8_LAS bf16x8*)(lds + PG8_SB(b, h) + boff + n * 2048 + k * 1024); } while (0)
; #define PG8_MMA(ai, bj, At, Bt) do { __builtin_amdgcn_s_setprio(1); _Pragma("unroll") for (int m = 0; m < 4; ++m) _Pragma("unroll") for (int n = 0; n < 2; ++n) _Pragma("unroll") for (int k = 0; k < 2; ++k) \
;         acc[ai][bj][m][n] = __builtin_amdgcn_mfma_f32_16x16x32_bf16(Bt[n][k], At[m][k], acc[ai][bj][m][n], 0, 0, 0); __builtin_amdgcn_s_setprio(0); } while (0)
; #define PG8_BAR __builtin_amdgcn_s_barrier()
; template <class Epi, class Sched, bool ALIGN_EPI = false, bool SP2 = false>
; __device__ __forceinline__ void gemm_phase(PG8_LAS unsigned char* lds, const Gemm g, const Sched& S, const Epi& E) {
;     ...
;             if constexpr (SP2) {
;             PG8_LDB(B0, 0, 0); PG8_LDB(B1, 0, 1); PG8_SCHED; PG8_LDA(At, 0, 0); PG8_STAGE(PG8_SA(1, 1), a1 + hstep, voffA);
;             PG8_WAIT_V(8); PG8_WAIT_L(0); PG8_BAR; PG8_MMA(0, 0, At, B0); PG8_MMA(0, 1, At, B1); PG8_BAR; PG8_SCHED;
;             PG8_LDA(At, 0, 1); PG8_STAGE(PG8_SB(0, 0), b2, voffB); PG8_STAGE(PG8_SB(0, 1), b2 + hstep, voffB); PG8_STAGE(PG8_SA(0, 0), a2, voffA);
;             PG8_WAIT_V(8); PG8_WAIT_L(0); PG8_BAR; PG8_MMA(1, 0, At, B0); PG8_MMA(1, 1, At, B1); PG8_BAR; PG8_SCHED;
;             PG8_LDB(B0, 1, 0); PG8_LDB(B1, 1, 1); PG8_SCHED; PG8_LDA(At, 1, 0); PG8_STAGE(PG8_SA(0, 1), a2 + hstep, voffA);
;             PG8_WAIT_V(8); PG8_WAIT_L(0); PG8_BAR; PG8_MMA(0, 0, At, B0); PG8_MMA(0, 1, At, B1); PG8_BAR; PG8_SCHED;
;             PG8_LDA(At, 1, 1); PG8_STAGE(PG8_SB(1, 0), b3, voffB); PG8_STAGE(PG8_SB(1, 1), b3 + hstep, voffB); PG8_STAGE(PG8_SA(1, 0), a3, voffA);
;             PG8_WAIT_V(8); PG8_WAIT_L(0); PG8_BAR; PG8_MMA(1, 0, At, B0); PG8_MMA(1, 1, At, B1); PG8_BAR; PG8_SCHED;
	s_setprio 1
	s_waitcnt lgkmcnt(0)
	v_mfma_f32_16x16x32_bf16 v[60:63], v[150:153], v[182:185], v[60:63]
	v_mfma_f32_16x16x32_bf16 v[56:59], v[158:161], v[182:185], v[56:59]
	v_mfma_f32_16x16x32_bf16 v[44:47], v[150:153], v[190:193], v[44:47]
	v_mfma_f32_16x16x32_bf16 v[40:43], v[158:161], v[190:193], v[40:43]
	v_mfma_f32_16x16x32_bf16 v[28:31], v[150:153], v[198:201], v[28:31]
	v_mfma_f32_16x16x32_bf16 v[24:27], v[158:161], v[198:201], v[24:27]
	v_mfma_f32_16x16x32_bf16 v[12:15], v[150:153], v[206:209], v[12:15]
	v_mfma_f32_16x16x32_bf16 v[8:11], v[158:161], v[206:209], v[8:11]
	v_mfma_f32_16x16x32_bf16 v[60:63], v[154:157], v[186:189], v[60:63]
	v_mfma_f32_16x16x32_bf16 v[56:59], v[162:165], v[186:189], v[56:59]
	v_mfma_f32_16x16x32_bf16 v[44:47], v[154:157], v[194:197], v[44:47]
	v_mfma_f32_16x16x32_bf16 v[40:43], v[162:165], v[194:197], v[40:43]
	v_mfma_f32_16x16x32_bf16 v[28:31], v[154:157], v[202:205], v[28:31]
	v_mfma_f32_16x16x32_bf16 v[24:27], v[162:165], v[202:205], v[24:27]
	v_mfma_f32_16x16x32_bf16 v[12:15], v[154:157], v[210:213], v[12:15]
	v_mfma_f32_16x16x32_bf16 v[8:11], v[162:165], v[210:213], v[8:11]
	v_mfma_f32_16x16x32_bf16 v[52:55], v[166:169], v[182:185], v[52:55]
	v_mfma_f32_16x16x32_bf16 v[48:51], v[174:177], v[182:185], v[48:51]
	v_mfma_f32_16x16x32_bf16 v[36:39], v[166:169], v[190:193], v[36:39]
	v_mfma_f32_16x16x32_bf16 v[32:35], v[174:177], v[190:193], v[32:35]
	v_mfma_f32_16x16x32_bf16 v[20:23], v[166:169], v[198:201], v[20:23]
	v_mfma_f32_16x16x32_bf16 v[16:19], v[174:177], v[198:201], v[16:19]
	v_mfma_f32_16x16x32_bf16 v[4:7], v[166:169], v[206:209], v[4:7]
	v_mfma_f32_16x16x32_bf16 v[0:3], v[174:177], v[206:209], v[0:3]
	v_mfma_f32_16x16x32_bf16 v[52:55], v[170:173], v[186:189], v[52:55]
	v_mfma_f32_16x16x32_bf16 v[48:51], v[178:181], v[186:189], v[48:51]
	v_mfma_f32_16x16x32_bf16 v[36:39], v[170:173], v[194:197], v[36:39]
	v_mfma_f32_16x16x32_bf16 v[32:35], v[178:181], v[194:197], v[32:35]
	v_mfma_f32_16x16x32_bf16 v[20:23], v[170:173], v[202:205], v[20:23]
	v_mfma_f32_16x16x32_bf16 v[16:19], v[178:181], v[202:205], v[16:19]
	v_mfma_f32_16x16x32_bf16 v[4:7], v[170:173], v[210:213], v[4:7]
	v_mfma_f32_16x16x32_bf16 v[0:3], v[178:181], v[210:213], v[0:3]
	s_setprio 0
	s_barrier
	s_add_i32 s35, 0, 0x18000
	v_add_u32_e32 v149, s35, v146
	s_add_i32 s54, 0, 0x1c000
	ds_read_b128 v[150:153], v149
	ds_read_b128 v[154:157], v149 offset:1024
	ds_read_b128 v[158:161], v149 offset:2048
	ds_read_b128 v[162:165], v149 offset:3072
	v_add_u32_e32 v149, s54, v146
	ds_read_b128 v[166:169], v149
	ds_read_b128 v[170:173], v149 offset:1024
	ds_read_b128 v[174:177], v149 offset:2048
	ds_read_b128 v[178:181], v149 offset:3072
	s_add_u32 s12, s12, 0x80000
	s_addc_u32 s13, s13, 0
	s_mov_b32 m0, s27
	v_lshl_add_u64 v[220:221], s[12:13], 0, v[130:131]
	ds_read_b128 v[182:185], v148 offset:32768
	ds_read_b128 v[186:189], v148 offset:33792
	ds_read_b128 v[190:193], v148 offset:34816
	ds_read_b128 v[194:197], v148 offset:35840
	ds_read_b128 v[198:201], v148 offset:36864
	ds_read_b128 v[202:205], v148 offset:37888
	ds_read_b128 v[206:209], v148 offset:38912
	ds_read_b128 v[210:213], v148 offset:39936
	global_load_lds_dwordx4 v[220:221], off
	v_lshl_add_u64 v[220:221], s[12:13], 0, v[132:133]
	s_mov_b32 m0, s28
	s_nop 0
	global_load_lds_dwordx4 v[220:221], off
	s_waitcnt vmcnt(8)
	s_waitcnt lgkmcnt(0)
	s_barrier
	s_setprio 1
	s_waitcnt lgkmcnt(0)
	v_mfma_f32_16x16x32_bf16 v[124:127], v[150:153], v[182:185], v[124:127]
	v_mfma_f32_16x16x32_bf16 v[120:123], v[158:161], v[182:185], v[120:123]
	v_mfma_f32_16x16x32_bf16 v[108:111], v[150:153], v[190:193], v[108:111]
	v_mfma_f32_16x16x32_bf16 v[104:107], v[158:161], v[190:193], v[104:107]
	v_mfma_f32_16x16x32_bf16 v[92:95], v[150:153], v[198:201], v[92:95]
	v_mfma_f32_16x16x32_bf16 v[88:91], v[158:161], v[198:201], v[88:91]
	v_mfma_f32_16x16x32_bf16 v[76:79], v[150:153], v[206:209], v[76:79]
	v_mfma_f32_16x16x32_bf16 v[72:75], v[158:161], v[206:209], v[72:75]
	v_mfma_f32_16x16x32_bf16 v[124:127], v[154:157], v[186:189], v[124:127]
	v_mfma_f32_16x16x32_bf16 v[120:123], v[162:165], v[186:189], v[120:123]
	v_mfma_f32_16x16x32_bf16 v[108:111], v[154:157], v[194:197], v[108:111]
	v_mfma_f32_16x16x32_bf16 v[104:107], v[162:165], v[194:197], v[104:107]
	v_mfma_f32_16x16x32_bf16 v[92:95], v[154:157], v[202:205], v[92:95]
	v_mfma_f32_16x16x32_bf16 v[88:91], v[162:165], v[202:205], v[88:91]
	v_mfma_f32_16x16x32_bf16 v[76:79], v[154:157], v[210:213], v[76:79]
	v_mfma_f32_16x16x32_bf16 v[72:75], v[162:165], v[210:213], v[72:75]
	v_mfma_f32_16x16x32_bf16 v[116:119], v[166:169], v[182:185], v[116:119]
	v_mfma_f32_16x16x32_bf16 v[112:115], v[174:177], v[182:185], v[112:115]
	v_mfma_f32_16x16x32_bf16 v[100:103], v[166:169], v[190:193], v[100:103]
	v_mfma_f32_16x16x32_bf16 v[96:99], v[174:177], v[190:193], v[96:99]
	v_mfma_f32_16x16x32_bf16 v[84:87], v[166:169], v[198:201], v[84:87]
	v_mfma_f32_16x16x32_bf16 v[80:83], v[174:177], v[198:201], v[80:83]
	v_mfma_f32_16x16x32_bf16 v[68:71], v[166:169], v[206:209], v[68:71]
	v_mfma_f32_16x16x32_bf16 v[64:67], v[174:177], v[206:209], v[64:67]
	v_mfma_f32_16x16x32_bf16 v[116:119], v[170:173], v[186:189], v[116:119]
	v_mfma_f32_16x16x32_bf16 v[112:115], v[178:181], v[186:189], v[112:115]
	v_mfma_f32_16x16x32_bf16 v[100:103], v[170:173], v[194:197], v[100:103]
	v_mfma_f32_16x16x32_bf16 v[96:99], v[178:181], v[194:197], v[96:99]
	v_mfma_f32_16x16x32_bf16 v[84:87], v[170:173], v[202:205], v[84:87]
	v_mfma_f32_16x16x32_bf16 v[80:83], v[178:181], v[202:205], v[80:83]
	v_mfma_f32_16x16x32_bf16 v[68:71], v[170:173], v[210:213], v[68:71]
	v_mfma_f32_16x16x32_bf16 v[64:67], v[178:181], v[210:213], v[64:67]
	s_setprio 0
	s_barrier
; #define PG8_STAGE(bufoff, gbase, voff) do { _Pragma("unroll") for (int _i = 0; _i < 2; ++_i) \
;         __builtin_amdgcn_global_load_lds((const unsigned*)((const char*)(gbase) + (voff)[_i]), (PG8_LAS unsigned*)(lds + (bufoff) + ldsw + _i * 8192), 16, 0, 0); } while (0)
; #define PG8_LDA(dst, b, h) do { _Pragma("unroll") for (int m = 0; m < 4; ++m) _Pragma("unroll") for (int k = 0; k < 2; ++k) dst[m][k] = *(const PG8_LAS bf16x8*)(lds + PG8_SA(b, h) + aoff + m * 2048 + k * 1024); } while (0)
; #define PG8_LDB(dst, b, h) do { _Pragma("unroll") for (int n = 0; n < 2; ++n) _Pragma("unroll") for (int k = 0; k < 2; ++k) dst[n][k] = *(const PG8_LAS bf16x8*)(lds + PG8_SB(b, h) + boff + n * 2048 + k * 1024); } while (0)
; #define PG8_MMA(ai, bj, At, Bt) do { __builtin_amdgcn_s_setprio(1); _Pragma("unroll") for (int m = 0; m < 4; ++m) _Pragma("unroll") for (int n = 0; n < 2; ++n) _Pragma("unroll") for (int k = 0; k < 2; ++k) \
;         acc[ai][bj][m][n] = __builtin_amdgcn_mfma_f32_16x16x32_bf16(Bt[n][k], At[m][k], acc[ai][bj][m][n], 0, 0, 0); __builtin_amdgcn_s_setprio(0); } while (0)
; #define PG8_BAR __builtin_amdgcn_s_barrier()
; template <class Epi, class Sched, bool ALIGN_EPI = false, bool SP2 = false>
; __device__ __forceinline__ void gemm_phase(PG8_LAS unsigned char* lds, const Gemm g, const Sched& S, const Epi& E) {
;     ...
;             if constexpr (SP2) {
;             PG8_LDB(B0, 0, 0); PG8_LDB(B1, 0, 1); PG8_SCHED; PG8_LDA(At, 0, 0); PG8_STAGE(PG8_SA(1, 1), a1 + hstep, voffA);
;             PG8_WAIT_V(8); PG8_WAIT_L(0); PG8_BAR; PG8_MMA(0, 0, At, B0); PG8_MMA(0, 1, At, B1); PG8_BAR; PG8_SCHED;
;             PG8_LDA(At, 0, 1); PG8_STAGE(PG8_SB(0, 0), b2, voffB); PG8_STAGE(PG8_SB(0, 1), b2 + hstep, voffB); PG8_STAGE(PG8_SA(0, 0), a2, voffA);
;             PG8_WAIT_V(8); PG8_WAIT_L(0); PG8_BAR; PG8_MMA(1, 0, At, B0); PG8_MMA(1, 1, At, B1); PG8_BAR; PG8_SCHED;
;             PG8_LDB(B0, 1, 0); PG8_LDB(B1, 1, 1); PG8_SCHED; PG8_LDA(At, 1, 0); PG8_STAGE(PG8_SA(0, 1), a2 + hstep, voffA);
;             PG8_WAIT_V(8); PG8_WAIT_L(0); PG8_BAR; PG8_MMA(0, 0, At, B0); PG8_MMA(0, 1, At, B1); PG8_BAR; PG8_SCHED;
;             PG8_LDA(At, 1, 1); PG8_STAGE(PG8_SB(1, 0), b3, voffB); PG8_STAGE(PG8_SB(1, 1), b3 + hstep, voffB); PG8_STAGE(PG8_SA(1, 0), a3, voffA);
;             PG8_WAIT_V(8); PG8_WAIT_L(0); PG8_BAR; PG8_MMA(1, 0, At, B0); PG8_MMA(1, 1, At, B1); PG8_BAR; PG8_SCHED;
	s_add_i32 s12, s35, s24
	v_lshl_add_u64 v[142:143], v[142:143], 0, s[84:85]
	s_mov_b32 m0, s12
	ds_read_b128 v[182:185], v148 offset:49152
	ds_read_b128 v[186:189], v148 offset:50176
	ds_read_b128 v[190:193], v148 offset:51200
	ds_read_b128 v[194:197], v148 offset:52224
	ds_read_b128 v[198:201], v148 offset:53248
	ds_read_b128 v[202:205], v148 offset:54272
	ds_read_b128 v[206:209], v148 offset:55296
	ds_read_b128 v[210:213], v148 offset:56320
	global_load_lds_dwordx4 v[142:143], off
	s_add_i32 m0, s12, 0x2000
	s_add_u32 s10, s10, 0x80080
	v_lshl_add_u64 v[142:143], v[214:215], 0, s[84:85]
	s_addc_u32 s11, s11, 0
	s_add_i32 s12, s54, s24
	global_load_lds_dwordx4 v[142:143], off
	v_lshl_add_u64 v[142:143], s[10:11], 0, v[128:129]
	s_mov_b32 m0, s12
	s_nop 0
	global_load_lds_dwordx4 v[142:143], off
	v_lshl_add_u64 v[142:143], s[10:11], 0, v[134:135]
	s_add_i32 m0, s12, 0x2000
	s_nop 0
	global_load_lds_dwordx4 v[142:143], off
	v_lshl_add_u64 v[142:143], v[216:217], 0, s[84:85]
	s_mov_b32 m0, s29
	s_nop 0
	global_load_lds_dwordx4 v[142:143], off
	v_lshl_add_u64 v[142:143], v[218:219], 0, s[84:85]
	s_mov_b32 m0, s90
	s_nop 0
	global_load_lds_dwordx4 v[142:143], off
	s_waitcnt vmcnt(8)
	s_waitcnt lgkmcnt(0)
	s_barrier
	s_setprio 1
	s_waitcnt lgkmcnt(0)
	v_mfma_f32_16x16x32_bf16 v[60:63], v[150:153], v[182:185], v[60:63]
	v_mfma_f32_16x16x32_bf16 v[56:59], v[158:161], v[182:185], v[56:59]
	v_mfma_f32_16x16x32_bf16 v[44:47], v[150:153], v[190:193], v[44:47]
	v_mfma_f32_16x16x32_bf16 v[40:43], v[158:161], v[190:193], v[40:43]
	v_mfma_f32_16x16x32_bf16 v[28:31], v[150:153], v[198:201], v[28:31]
	v_mfma_f32_16x16x32_bf16 v[24:27], v[158:161], v[198:201], v[24:27]
	v_mfma_f32_16x16x32_bf16 v[12:15], v[150:153], v[206:209], v[12:15]
	v_mfma_f32_16x16x32_bf16 v[8:11], v[158:161], v[206:209], v[8:11]
	v_mfma_f32_16x16x32_bf16 v[60:63], v[154:157], v[186:189], v[60:63]
	v_mfma_f32_16x16x32_bf16 v[56:59], v[162:165], v[186:189], v[56:59]
	v_mfma_f32_16x16x32_bf16 v[44:47], v[154:157], v[194:197], v[44:47]
	v_mfma_f32_16x16x32_bf16 v[40:43], v[162:165], v[194:197], v[40:43]
	v_mfma_f32_16x16x32_bf16 v[28:31], v[154:157], v[202:205], v[28:31]
	v_mfma_f32_16x16x32_bf16 v[24:27], v[162:165], v[202:205], v[24:27]
	v_mfma_f32_16x16x32_bf16 v[12:15], v[154:157], v[210:213], v[12:15]
	v_mfma_f32_16x16x32_bf16 v[8:11], v[162:165], v[210:213], v[8:11]
	v_mfma_f32_16x16x32_bf16 v[52:55], v[166:169], v[182:185], v[52:55]
	v_mfma_f32_16x16x32_bf16 v[48:51], v[174:177], v[182:185], v[48:51]
	v_mfma_f32_16x16x32_bf16 v[36:39], v[166:169], v[190:193], v[36:39]
	v_mfma_f32_16x16x32_bf16 v[32:35], v[174:177], v[190:193], v[32:35]
	v_mfma_f32_16x16x32_bf16 v[20:23], v[166:169], v[198:201], v[20:23]
	v_mfma_f32_16x16x32_bf16 v[16:19], v[174:177], v[198:201], v[16:19]
	v_mfma_f32_16x16x32_bf16 v[4:7], v[166:169], v[206:209], v[4:7]
	v_mfma_f32_16x16x32_bf16 v[0:3], v[174:177], v[206:209], v[0:3]
	v_mfma_f32_16x16x32_bf16 v[52:55], v[170:173], v[186:189], v[52:55]
	v_mfma_f32_16x16x32_bf16 v[48:51], v[178:181], v[186:189], v[48:51]
	v_mfma_f32_16x16x32_bf16 v[36:39], v[170:173], v[194:197], v[36:39]
	v_mfma_f32_16x16x32_bf16 v[32:35], v[178:181], v[194:197], v[32:35]
	v_mfma_f32_16x16x32_bf16 v[20:23], v[170:173], v[202:205], v[20:23]
	v_mfma_f32_16x16x32_bf16 v[16:19], v[178:181], v[202:205], v[16:19]
	v_mfma_f32_16x16x32_bf16 v[4:7], v[170:173], v[210:213], v[4:7]
	v_mfma_f32_16x16x32_bf16 v[0:3], v[178:181], v[210:213], v[0:3]
	s_setprio 0
	s_barrier
	s_add_i32 s34, s34, 2
	s_add_u32 s8, s8, 0x100
	s_addc_u32 s9, s9, 0
	s_add_u32 vcc_lo, vcc_lo, 0x100
	s_addc_u32 vcc_hi, vcc_hi, 0
	s_cmp_gt_u32 s34, 29
	s_cbranch_scc0 .LBB0_704
	s_and_b64 vcc, exec, s[4:5]
	s_cbranch_vccz .LBB0_707
	s_barrier

; #define PG8_STAGE(bufoff, gbase, voff) do { _Pragma("unroll") for (int _i = 0; _i < 2; ++_i) \
;         __builtin_amdgcn_global_load_lds((const unsigned*)((const char*)(gbase) + (voff)[_i]), (PG8_LAS unsigned*)(lds + (bufoff) + ldsw + _i * 8192), 16, 0, 0); } while (0)
; #define PG8_LDA(dst, b, h) do { _Pragma("unroll") for (int m = 0; m < 4; ++m) _Pragma("unroll") for (int k = 0; k < 2; ++k) dst[m][k] = *(const PG8_LAS bf16x8*)(lds + PG8_SA(b, h) + aoff + m * 2048 + k * 1024); } while (0)
; #define PG8_LDB(dst, b, h) do { _Pragma("unroll") for (int n = 0; n < 2; ++n) _Pragma("unroll") for (int k = 0; k < 2; ++k) dst[n][k] = *(const PG8_LAS bf16x8*)(lds + PG8_SB(b, h) + boff + n * 2048 + k * 1024); } while (0)
; #define PG8_MMA(ai, bj, At, Bt) do { __builtin_amdgcn_s_setprio(1); _Pragma("unroll") for (int m = 0; m < 4; ++m) _Pragma("unroll") for (int n = 0; n < 2; ++n) _Pragma("unroll") for (int k = 0; k < 2; ++k) \
;         acc[ai][bj][m][n] = __builtin_amdgcn_mfma_f32_16x16x32_bf16(Bt[n][k], At[m][k], acc[ai][bj][m][n], 0, 0, 0); __builtin_amdgcn_s_setprio(0); } while (0)
; #define PG8_WAIT_V(n) asm volatile("s_waitcnt vmcnt(" #n ")" ::: "memory")
; #define PG8_WAIT_L(n) asm volatile("s_waitcnt lgkmcnt(" #n ")" ::: "memory")
; template <class Epi, class Sched, bool ALIGN_EPI = false, bool SP2 = false>
; __device__ __forceinline__ void gemm_phase(PG8_LAS unsigned char* lds, const Gemm g, const Sched& S, const Epi& E) {
;     ...
;             const bool last = (t == nt - 2);
;             const char* a1 = cA + (size_t)(t + 1) * kstep;
;             const char* a2 = last ? nA : cA + (size_t)(t + 2) * kstep; const char* b2 = last ? nB : cB + (size_t)(t + 2) * kstep;
;             const char* a3 = a2 + kstep; const char* b3 = b2 + kstep;
;             if (last && has_next) S.a_ready(nxt);
;             if constexpr (SP2) {
;             PG8_LDB(B0, 0, 0); PG8_LDB(B1, 0, 1); PG8_SCHED; PG8_LDA(At, 0, 0); PG8_STAGE(PG8_SA(1, 1), a1 + hstep, voffA);
;             PG8_WAIT_V(8); PG8_WAIT_L(0); PG8_BAR; PG8_MMA(0, 0, At, B0); PG8_MMA(0, 1, At, B1); PG8_BAR; PG8_SCHED;
;             PG8_LDA(At, 0, 1); PG8_STAGE(PG8_SB(0, 0), b2, voffB); PG8_STAGE(PG8_SB(0, 1), b2 + hstep, voffB); PG8_STAGE(PG8_SA(0, 0), a2, voffA);
;             PG8_WAIT_V(8); PG8_WAIT_L(0); PG8_BAR; PG8_MMA(1, 0, At, B0); PG8_MMA(1, 1, At, B1); PG8_BAR; PG8_SCHED;
.LBB0_783:
	s_add_u32 vcc_lo, s38, 0x100
	s_addc_u32 vcc_hi, s39, 0
	s_add_i32 s54, 0, 0x10000
	s_cmpk_eq_i32 s35, 0x7c
	s_cselect_b32 s15, s1, vcc_hi
	s_cselect_b32 s14, s9, vcc_lo
	v_add_u32_e32 v140, s54, v143
	s_cselect_b32 s5, s7, s34
	s_cselect_b32 s4, s30, s31
	s_add_i32 s80, 0, 0x14000
	ds_read_b128 v[136:139], v140
	ds_read_b128 v[148:151], v140 offset:1024
	ds_read_b128 v[152:155], v140 offset:2048
	ds_read_b128 v[156:159], v140 offset:3072
	v_add_u32_e32 v140, s80, v143
	ds_read_b128 v[160:163], v140
	ds_read_b128 v[164:167], v140 offset:1024
	ds_read_b128 v[168:171], v140 offset:2048
	ds_read_b128 v[172:175], v140 offset:3072
	v_lshl_add_u64 v[140:141], s[38:39], 0, v[132:133]
	s_add_i32 m0, s91, 0xc000
	ds_read_b128 v[176:179], v146
	ds_read_b128 v[180:183], v146 offset:1024
	ds_read_b128 v[184:187], v146 offset:2048
	ds_read_b128 v[188:191], v146 offset:3072
	ds_read_b128 v[192:195], v146 offset:4096
	ds_read_b128 v[196:199], v146 offset:5120
	ds_read_b128 v[200:203], v146 offset:6144
	ds_read_b128 v[204:207], v146 offset:7168
	global_load_lds_dwordx4 v[140:141], off
	v_lshl_add_u64 v[140:141], s[38:39], 0, v[134:135]
	s_add_i32 m0, s91, 0xe000
	s_nop 0
	global_load_lds_dwordx4 v[140:141], off
	s_waitcnt vmcnt(8)
	s_waitcnt lgkmcnt(0)
	s_barrier
	s_setprio 1
	s_waitcnt lgkmcnt(0)
	v_mfma_f32_16x16x32_bf16 v[124:127], v[136:139], v[176:179], v[124:127]
	v_mfma_f32_16x16x32_bf16 v[120:123], v[152:155], v[176:179], v[120:123]
	v_mfma_f32_16x16x32_bf16 v[108:111], v[136:139], v[184:187], v[108:111]
	v_mfma_f32_16x16x32_bf16 v[104:107], v[152:155], v[184:187], v[104:107]
	v_mfma_f32_16x16x32_bf16 v[92:95], v[136:139], v[192:195], v[92:95]
	v_mfma_f32_16x16x32_bf16 v[88:91], v[152:155], v[192:195], v[88:91]
	v_mfma_f32_16x16x32_bf16 v[76:79], v[136:139], v[200:203], v[76:79]
	v_mfma_f32_16x16x32_bf16 v[72:75], v[152:155], v[200:203], v[72:75]
	v_mfma_f32_16x16x32_bf16 v[124:127], v[148:151], v[180:183], v[124:127]
	v_mfma_f32_16x16x32_bf16 v[120:123], v[156:159], v[180:183], v[120:123]
	v_mfma_f32_16x16x32_bf16 v[108:111], v[148:151], v[188:191], v[108:111]
	v_mfma_f32_16x16x32_bf16 v[104:107], v[156:159], v[188:191], v[104:107]
	v_mfma_f32_16x16x32_bf16 v[92:95], v[148:151], v[196:199], v[92:95]
	v_mfma_f32_16x16x32_bf16 v[88:91], v[156:159], v[196:199], v[88:91]
	v_mfma_f32_16x16x32_bf16 v[76:79], v[148:151], v[204:207], v[76:79]
	v_mfma_f32_16x16x32_bf16 v[72:75], v[156:159], v[204:207], v[72:75]
	v_mfma_f32_16x16x32_bf16 v[116:119], v[160:163], v[176:179], v[116:119]
	v_mfma_f32_16x16x32_bf16 v[112:115], v[168:171], v[176:179], v[112:115]
	v_mfma_f32_16x16x32_bf16 v[100:103], v[160:163], v[184:187], v[100:103]
	v_mfma_f32_16x16x32_bf16 v[96:99], v[168:171], v[184:187], v[96:99]
	v_mfma_f32_16x16x32_bf16 v[84:87], v[160:163], v[192:195], v[84:87]
	v_mfma_f32_16x16x32_bf16 v[80:83], v[168:171], v[192:195], v[80:83]
	v_mfma_f32_16x16x32_bf16 v[68:71], v[160:163], v[200:203], v[68:71]
	v_mfma_f32_16x16x32_bf16 v[64:67], v[168:171], v[200:203], v[64:67]
	v_mfma_f32_16x16x32_bf16 v[116:119], v[164:167], v[180:183], v[116:119]
	v_mfma_f32_16x16x32_bf16 v[112:115], v[172:175], v[180:183], v[112:115]
	v_mfma_f32_16x16x32_bf16 v[100:103], v[164:167], v[188:191], v[100:103]
	v_mfma_f32_16x16x32_bf16 v[96:99], v[172:175], v[188:191], v[96:99]
	v_mfma_f32_16x16x32_bf16 v[84:87], v[164:167], v[196:199], v[84:87]
	v_mfma_f32_16x16x32_bf16 v[80:83], v[172:175], v[196:199], v[80:83]
	v_mfma_f32_16x16x32_bf16 v[68:71], v[164:167], v[204:207], v[68:71]
	v_mfma_f32_16x16x32_bf16 v[64:67], v[172:175], v[204:207], v[64:67]
	s_setprio 0
	s_barrier
	s_add_i32 s38, s54, s23
	v_lshl_add_u64 v[140:141], s[4:5], 0, v[128:129]
	s_mov_b32 m0, s38
	ds_read_b128 v[176:179], v146 offset:16384
	ds_read_b128 v[180:183], v146 offset:17408
	ds_read_b128 v[184:187], v146 offset:18432
	ds_read_b128 v[188:191], v146 offset:19456
	ds_read_b128 v[192:195], v146 offset:20480
	ds_read_b128 v[196:199], v146 offset:21504
	ds_read_b128 v[200:203], v146 offset:22528
	ds_read_b128 v[204:207], v146 offset:23552
	global_load_lds_dwordx4 v[140:141], off
	s_add_i32 m0, s38, 0x2000
	s_add_u32 s38, s4, 0x200000
	v_lshl_add_u64 v[208:209], s[4:5], 0, v[130:131]
	s_addc_u32 s39, s5, 0
	s_add_i32 s54, s80, s23
	global_load_lds_dwordx4 v[208:209], off
	v_lshl_add_u64 v[210:211], s[38:39], 0, v[128:129]
	s_mov_b32 m0, s54
	v_lshl_add_u64 v[212:213], s[14:15], 0, v[130:131]
	global_load_lds_dwordx4 v[210:211], off
	v_lshl_add_u64 v[210:211], s[38:39], 0, v[130:131]
	s_add_i32 m0, s54, 0x2000
	s_nop 0
	global_load_lds_dwordx4 v[210:211], off
	v_lshl_add_u64 v[210:211], s[14:15], 0, v[128:129]
	s_mov_b32 m0, s91
	s_nop 0
	global_load_lds_dwordx4 v[210:211], off
	s_mov_b32 m0, s24
	s_nop 0
	global_load_lds_dwordx4 v[212:213], off
	s_waitcnt vmcnt(8)
	s_waitcnt lgkmcnt(0)
	s_barrier
; #define PG8_STAGE(bufoff, gbase, voff) do { _Pragma("unroll") for (int _i = 0; _i < 2; ++_i) \
;         __builtin_amdgcn_global_load_lds((const unsigned*)((const char*)(gbase) + (voff)[_i]), (PG8_LAS unsigned*)(lds + (bufoff) + ldsw + _i * 8192), 16, 0, 0); } while (0)
; #define PG8_LDA(dst, b, h) do { _Pragma("unroll") for (int m = 0; m < 4; ++m) _Pragma("unroll") for (int k = 0; k < 2; ++k) dst[m][k] = *(const PG8_LAS bf16x8*)(lds + PG8_SA(b, h) + aoff + m * 2048 + k * 1024); } while (0)
; #define PG8_LDB(dst, b, h) do { _Pragma("unroll") for (int n = 0; n < 2; ++n) _Pragma("unroll") for (int k = 0; k < 2; ++k) dst[n][k] = *(const PG8_LAS bf16x8*)(lds + PG8_SB(b, h) + boff + n * 2048 + k * 1024); } while (0)
; #define PG8_MMA(ai, bj, At, Bt) do { __builtin_amdgcn_s_setprio(1); _Pragma("unroll") for (int m = 0; m < 4; ++m) _Pragma("unroll") for (int n = 0; n < 2; ++n) _Pragma("unroll") for (int k = 0; k < 2; ++k) \
;         acc[ai][bj][m][n] = __builtin_amdgcn_mfma_f32_16x16x32_bf16(Bt[n][k], At[m][k], acc[ai][bj][m][n], 0, 0, 0); __builtin_amdgcn_s_setprio(0); } while (0)
; #define PG8_WAIT_V(n) asm volatile("s_waitcnt vmcnt(" #n ")" ::: "memory")
; #define PG8_WAIT_L(n) asm volatile("s_waitcnt lgkmcnt(" #n ")" ::: "memory")
; #define PG8_BAR __builtin_amdgcn_s_barrier()
; #define PG8_SCHED __builtin_amdgcn_sched_barrier(0)
; template <class Epi, class Sched, bool ALIGN_EPI = false, bool SP2 = false>
; __device__ __forceinline__ void gemm_phase(PG8_LAS unsigned char* lds, const Gemm g, const Sched& S, const Epi& E) {
;     ...
;             PG8_WAIT_V(8); PG8_WAIT_L(0); PG8_BAR; PG8_MMA(1, 0, At, B0); PG8_MMA(1, 1, At, B1); PG8_BAR; PG8_SCHED;
;             PG8_LDB(B0, 1, 0); PG8_LDB(B1, 1, 1); PG8_SCHED; PG8_LDA(At, 1, 0); PG8_STAGE(PG8_SA(0, 1), a2 + hstep, voffA);
;             PG8_WAIT_V(8); PG8_WAIT_L(0); PG8_BAR; PG8_MMA(0, 0, At, B0); PG8_MMA(0, 1, At, B1); PG8_BAR; PG8_SCHED;
	s_setprio 1
	s_waitcnt lgkmcnt(0)
	v_mfma_f32_16x16x32_bf16 v[60:63], v[136:139], v[176:179], v[60:63]
	v_mfma_f32_16x16x32_bf16 v[56:59], v[152:155], v[176:179], v[56:59]
	v_mfma_f32_16x16x32_bf16 v[44:47], v[136:139], v[184:187], v[44:47]
	v_mfma_f32_16x16x32_bf16 v[40:43], v[152:155], v[184:187], v[40:43]
	v_mfma_f32_16x16x32_bf16 v[28:31], v[136:139], v[192:195], v[28:31]
	v_mfma_f32_16x16x32_bf16 v[24:27], v[152:155], v[192:195], v[24:27]
	v_mfma_f32_16x16x32_bf16 v[12:15], v[136:139], v[200:203], v[12:15]
	v_mfma_f32_16x16x32_bf16 v[8:11], v[152:155], v[200:203], v[8:11]
	v_mfma_f32_16x16x32_bf16 v[60:63], v[148:151], v[180:183], v[60:63]
	v_mfma_f32_16x16x32_bf16 v[56:59], v[156:159], v[180:183], v[56:59]
	v_mfma_f32_16x16x32_bf16 v[44:47], v[148:151], v[188:191], v[44:47]
	v_mfma_f32_16x16x32_bf16 v[40:43], v[156:159], v[188:191], v[40:43]
	v_mfma_f32_16x16x32_bf16 v[28:31], v[148:151], v[196:199], v[28:31]
	v_mfma_f32_16x16x32_bf16 v[24:27], v[156:159], v[196:199], v[24:27]
	v_mfma_f32_16x16x32_bf16 v[12:15], v[148:151], v[204:207], v[12:15]
	v_mfma_f32_16x16x32_bf16 v[8:11], v[156:159], v[204:207], v[8:11]
	v_mfma_f32_16x16x32_bf16 v[52:55], v[160:163], v[176:179], v[52:55]
	v_mfma_f32_16x16x32_bf16 v[48:51], v[168:171], v[176:179], v[48:51]
	v_mfma_f32_16x16x32_bf16 v[36:39], v[160:163], v[184:187], v[36:39]
	v_mfma_f32_16x16x32_bf16 v[32:35], v[168:171], v[184:187], v[32:35]
	v_mfma_f32_16x16x32_bf16 v[20:23], v[160:163], v[192:195], v[20:23]
	v_mfma_f32_16x16x32_bf16 v[16:19], v[168:171], v[192:195], v[16:19]
	v_mfma_f32_16x16x32_bf16 v[4:7], v[160:163], v[200:203], v[4:7]
	v_mfma_f32_16x16x32_bf16 v[0:3], v[168:171], v[200:203], v[0:3]
	v_mfma_f32_16x16x32_bf16 v[52:55], v[164:167], v[180:183], v[52:55]
	v_mfma_f32_16x16x32_bf16 v[48:51], v[172:175], v[180:183], v[48:51]
	v_mfma_f32_16x16x32_bf16 v[36:39], v[164:167], v[188:191], v[36:39]
	v_mfma_f32_16x16x32_bf16 v[32:35], v[172:175], v[188:191], v[32:35]
	v_mfma_f32_16x16x32_bf16 v[20:23], v[164:167], v[196:199], v[20:23]
	v_mfma_f32_16x16x32_bf16 v[16:19], v[172:175], v[196:199], v[16:19]
	v_mfma_f32_16x16x32_bf16 v[4:7], v[164:167], v[204:207], v[4:7]
	v_mfma_f32_16x16x32_bf16 v[0:3], v[172:175], v[204:207], v[0:3]
	s_setprio 0
	s_barrier
	s_add_i32 s38, 0, 0x18000
	v_add_u32_e32 v147, s38, v143
	s_add_i32 s39, 0, 0x1c000
	ds_read_b128 v[136:139], v147
	ds_read_b128 v[148:151], v147 offset:1024
	ds_read_b128 v[152:155], v147 offset:2048
	ds_read_b128 v[156:159], v147 offset:3072
	v_add_u32_e32 v147, s39, v143
	ds_read_b128 v[160:163], v147
	ds_read_b128 v[164:167], v147 offset:1024
	ds_read_b128 v[168:171], v147 offset:2048
	ds_read_b128 v[172:175], v147 offset:3072
	s_add_u32 s14, s14, 0x200000
	s_addc_u32 s15, s15, 0
	s_mov_b32 m0, s25
	v_lshl_add_u64 v[214:215], s[14:15], 0, v[128:129]
	ds_read_b128 v[176:179], v146 offset:32768
	ds_read_b128 v[180:183], v146 offset:33792
	ds_read_b128 v[184:187], v146 offset:34816
	ds_read_b128 v[188:191], v146 offset:35840
	ds_read_b128 v[192:195], v146 offset:36864
	ds_read_b128 v[196:199], v146 offset:37888
	ds_read_b128 v[200:203], v146 offset:38912
	ds_read_b128 v[204:207], v146 offset:39936
	global_load_lds_dwordx4 v[214:215], off
	v_lshl_add_u64 v[214:215], s[14:15], 0, v[130:131]
	s_mov_b32 m0, s26
	s_nop 0
	global_load_lds_dwordx4 v[214:215], off
	s_waitcnt vmcnt(8)
	s_waitcnt lgkmcnt(0)
	s_barrier
	s_setprio 1
	s_waitcnt lgkmcnt(0)
	v_mfma_f32_16x16x32_bf16 v[124:127], v[136:139], v[176:179], v[124:127]
	v_mfma_f32_16x16x32_bf16 v[120:123], v[152:155], v[176:179], v[120:123]
	v_mfma_f32_16x16x32_bf16 v[108:111], v[136:139], v[184:187], v[108:111]
	v_mfma_f32_16x16x32_bf16 v[104:107], v[152:155], v[184:187], v[104:107]
	v_mfma_f32_16x16x32_bf16 v[92:95], v[136:139], v[192:195], v[92:95]
	v_mfma_f32_16x16x32_bf16 v[88:91], v[152:155], v[192:195], v[88:91]
	v_mfma_f32_16x16x32_bf16 v[76:79], v[136:139], v[200:203], v[76:79]
	v_mfma_f32_16x16x32_bf16 v[72:75], v[152:155], v[200:203], v[72:75]
	v_mfma_f32_16x16x32_bf16 v[124:127], v[148:151], v[180:183], v[124:127]
	v_mfma_f32_16x16x32_bf16 v[120:123], v[156:159], v[180:183], v[120:123]
	v_mfma_f32_16x16x32_bf16 v[108:111], v[148:151], v[188:191], v[108:111]
	v_mfma_f32_16x16x32_bf16 v[104:107], v[156:159], v[188:191], v[104:107]
	v_mfma_f32_16x16x32_bf16 v[92:95], v[148:151], v[196:199], v[92:95]
	v_mfma_f32_16x16x32_bf16 v[88:91], v[156:159], v[196:199], v[88:91]
	v_mfma_f32_16x16x32_bf16 v[76:79], v[148:151], v[204:207], v[76:79]
	v_mfma_f32_16x16x32_bf16 v[72:75], v[156:159], v[204:207], v[72:75]
	v_mfma_f32_16x16x32_bf16 v[116:119], v[160:163], v[176:179], v[116:119]
	v_mfma_f32_16x16x32_bf16 v[112:115], v[168:171], v[176:179], v[112:115]
	v_mfma_f32_16x16x32_bf16 v[100:103], v[160:163], v[184:187], v[100:103]
	v_mfma_f32_16x16x32_bf16 v[96:99], v[168:171], v[184:187], v[96:99]
	v_mfma_f32_16x16x32_bf16 v[84:87], v[160:163], v[192:195], v[84:87]
	v_mfma_f32_16x16x32_bf16 v[80:83], v[168:171], v[192:195], v[80:83]
	v_mfma_f32_16x16x32_bf16 v[68:71], v[160:163], v[200:203], v[68:71]
	v_mfma_f32_16x16x32_bf16 v[64:67], v[168:171], v[200:203], v[64:67]
	v_mfma_f32_16x16x32_bf16 v[116:119], v[164:167], v[180:183], v[116:119]
	v_mfma_f32_16x16x32_bf16 v[112:115], v[172:175], v[180:183], v[112:115]
	v_mfma_f32_16x16x32_bf16 v[100:103], v[164:167], v[188:191], v[100:103]
	v_mfma_f32_16x16x32_bf16 v[96:99], v[172:175], v[188:191], v[96:99]
	v_mfma_f32_16x16x32_bf16 v[84:87], v[164:167], v[196:199], v[84:87]
	v_mfma_f32_16x16x32_bf16 v[80:83], v[172:175], v[196:199], v[80:83]
	v_mfma_f32_16x16x32_bf16 v[68:71], v[164:167], v[204:207], v[68:71]
	v_mfma_f32_16x16x32_bf16 v[64:67], v[172:175], v[204:207], v[64:67]
	s_setprio 0
	s_barrier
; #define PG8_STAGE(bufoff, gbase, voff) do { _Pragma("unroll") for (int _i = 0; _i < 2; ++_i) \
;         __builtin_amdgcn_global_load_lds((const unsigned*)((const char*)(gbase) + (voff)[_i]), (PG8_LAS unsigned*)(lds + (bufoff) + ldsw + _i * 8192), 16, 0, 0); } while (0)
; #define PG8_LDA(dst, b, h) do { _Pragma("unroll") for (int m = 0; m < 4; ++m) _Pragma("unroll") for (int k = 0; k < 2; ++k) dst[m][k] = *(const PG8_LAS bf16x8*)(lds + PG8_SA(b, h) + aoff + m * 2048 + k * 1024); } while (0)
; #define PG8_MMA(ai, bj, At, Bt) do { __builtin_amdgcn_s_setprio(1); _Pragma("unroll") for (int m = 0; m < 4; ++m) _Pragma("unroll") for (int n = 0; n < 2; ++n) _Pragma("unroll") for (int k = 0; k < 2; ++k) \
;         acc[ai][bj][m][n] = __builtin_amdgcn_mfma_f32_16x16x32_bf16(Bt[n][k], At[m][k], acc[ai][bj][m][n], 0, 0, 0); __builtin_amdgcn_s_setprio(0); } while (0)
; #define PG8_WAIT_V(n) asm volatile("s_waitcnt vmcnt(" #n ")" ::: "memory")
; #define PG8_WAIT_L(n) asm volatile("s_waitcnt lgkmcnt(" #n ")" ::: "memory")
; #define PG8_BAR __builtin_amdgcn_s_barrier()
; #define PG8_SCHED __builtin_amdgcn_sched_barrier(0)
; template <class Epi, class Sched, bool ALIGN_EPI = false, bool SP2 = false>
; __device__ __forceinline__ void gemm_phase(PG8_LAS unsigned char* lds, const Gemm g, const Sched& S, const Epi& E) {
;     ...
;             PG8_LDA(At, 1, 1); PG8_STAGE(PG8_SB(1, 0), b3, voffB); PG8_STAGE(PG8_SB(1, 1), b3 + hstep, voffB); PG8_STAGE(PG8_SA(1, 0), a3, voffA);
;             PG8_WAIT_V(8); PG8_WAIT_L(0); PG8_BAR; PG8_MMA(1, 0, At, B0); PG8_MMA(1, 1, At, B1); PG8_BAR; PG8_SCHED;
	s_add_i32 s14, s38, s23
	v_lshl_add_u64 v[140:141], v[140:141], 0, s[84:85]
	s_mov_b32 m0, s14
	ds_read_b128 v[176:179], v146 offset:49152
	ds_read_b128 v[180:183], v146 offset:50176
	ds_read_b128 v[184:187], v146 offset:51200
	ds_read_b128 v[188:191], v146 offset:52224
	ds_read_b128 v[192:195], v146 offset:53248
	ds_read_b128 v[196:199], v146 offset:54272
	ds_read_b128 v[200:203], v146 offset:55296
	ds_read_b128 v[204:207], v146 offset:56320
	global_load_lds_dwordx4 v[140:141], off
	s_add_i32 m0, s14, 0x2000
	s_add_u32 s4, s4, 0x200080
	v_lshl_add_u64 v[140:141], v[208:209], 0, s[84:85]
	s_addc_u32 s5, s5, 0
	s_add_i32 s14, s39, s23
	global_load_lds_dwordx4 v[140:141], off
	v_lshl_add_u64 v[140:141], s[4:5], 0, v[128:129]
	s_mov_b32 m0, s14
	s_nop 0
	global_load_lds_dwordx4 v[140:141], off
	v_lshl_add_u64 v[140:141], s[4:5], 0, v[130:131]
	s_add_i32 m0, s14, 0x2000
	s_nop 0
	global_load_lds_dwordx4 v[140:141], off
	v_lshl_add_u64 v[140:141], v[210:211], 0, s[84:85]
	s_mov_b32 m0, s20
	s_nop 0
	global_load_lds_dwordx4 v[140:141], off
	v_lshl_add_u64 v[140:141], v[212:213], 0, s[84:85]
	s_mov_b32 m0, s27
	s_nop 0
	global_load_lds_dwordx4 v[140:141], off
	s_waitcnt vmcnt(8)
	s_waitcnt lgkmcnt(0)
	s_barrier
	s_setprio 1
	s_waitcnt lgkmcnt(0)
	v_mfma_f32_16x16x32_bf16 v[60:63], v[136:139], v[176:179], v[60:63]
	v_mfma_f32_16x16x32_bf16 v[56:59], v[152:155], v[176:179], v[56:59]
	v_mfma_f32_16x16x32_bf16 v[44:47], v[136:139], v[184:187], v[44:47]
	v_mfma_f32_16x16x32_bf16 v[40:43], v[152:155], v[184:187], v[40:43]
	v_mfma_f32_16x16x32_bf16 v[28:31], v[136:139], v[192:195], v[28:31]
	v_mfma_f32_16x16x32_bf16 v[24:27], v[152:155], v[192:195], v[24:27]
	v_mfma_f32_16x16x32_bf16 v[12:15], v[136:139], v[200:203], v[12:15]
	v_mfma_f32_16x16x32_bf16 v[8:11], v[152:155], v[200:203], v[8:11]
	v_mfma_f32_16x16x32_bf16 v[60:63], v[148:151], v[180:183], v[60:63]
	v_mfma_f32_16x16x32_bf16 v[56:59], v[156:159], v[180:183], v[56:59]
	v_mfma_f32_16x16x32_bf16 v[44:47], v[148:151], v[188:191], v[44:47]
	v_mfma_f32_16x16x32_bf16 v[40:43], v[156:159], v[188:191], v[40:43]
	v_mfma_f32_16x16x32_bf16 v[28:31], v[148:151], v[196:199], v[28:31]
	v_mfma_f32_16x16x32_bf16 v[24:27], v[156:159], v[196:199], v[24:27]
	v_mfma_f32_16x16x32_bf16 v[12:15], v[148:151], v[204:207], v[12:15]
	v_mfma_f32_16x16x32_bf16 v[8:11], v[156:159], v[204:207], v[8:11]
	v_mfma_f32_16x16x32_bf16 v[52:55], v[160:163], v[176:179], v[52:55]
	v_mfma_f32_16x16x32_bf16 v[48:51], v[168:171], v[176:179], v[48:51]
	v_mfma_f32_16x16x32_bf16 v[36:39], v[160:163], v[184:187], v[36:39]
	v_mfma_f32_16x16x32_bf16 v[32:35], v[168:171], v[184:187], v[32:35]
	v_mfma_f32_16x16x32_bf16 v[20:23], v[160:163], v[192:195], v[20:23]
	v_mfma_f32_16x16x32_bf16 v[16:19], v[168:171], v[192:195], v[16:19]
	v_mfma_f32_16x16x32_bf16 v[4:7], v[160:163], v[200:203], v[4:7]
	v_mfma_f32_16x16x32_bf16 v[0:3], v[168:171], v[200:203], v[0:3]
	v_mfma_f32_16x16x32_bf16 v[52:55], v[164:167], v[180:183], v[52:55]
	v_mfma_f32_16x16x32_bf16 v[48:51], v[172:175], v[180:183], v[48:51]
	v_mfma_f32_16x16x32_bf16 v[36:39], v[164:167], v[188:191], v[36:39]
	v_mfma_f32_16x16x32_bf16 v[32:35], v[172:175], v[188:191], v[32:35]
	v_mfma_f32_16x16x32_bf16 v[20:23], v[164:167], v[196:199], v[20:23]
	v_mfma_f32_16x16x32_bf16 v[16:19], v[172:175], v[196:199], v[16:19]
	v_mfma_f32_16x16x32_bf16 v[4:7], v[164:167], v[204:207], v[4:7]
	v_mfma_f32_16x16x32_bf16 v[0:3], v[172:175], v[204:207], v[0:3]
	s_setprio 0
	s_barrier
	s_add_i32 s35, s35, 2
	s_add_u32 s31, s31, 0x100
	s_addc_u32 s34, s34, 0
	s_cmpk_gt_u32 s35, 0x7d
	s_mov_b64 s[38:39], vcc
	s_cbranch_scc0 .LBB0_783
	s_and_b64 vcc, exec, s[96:97]
	s_cbranch_vccz .LBB0_786
	s_barrier
